# HGRN rewritten: 4 prep waves (LDS-DMA staged, 64-step scan) + 4 MFMA waves, double-buffered swizzled LDS images, tr reads, 1 barrier per chunk; gMLP invariant loads hoisted; barrier poll sleep
# speedup vs baseline: 1.0274x; 1.0274x over previous
.Lh2_entry:
	v_readfirstlane_b32 s0, v200
	s_lshr_b32 s0, s0, 6
	s_lshr_b32 s8, s2, 3
	s_bfe_u32 s9, s2, 0x20001
	s_and_b32 s12, s2, 1
	s_cmp_ge_u32 s0, 4
	s_cbranch_scc1 .Lh2_mfma
.Lh2_prep:
	v_and_b32_e32 v244, 63, v200
	v_lshrrev_b32_e32 v245, 2, v244
	v_lshrrev_b32_e32 v243, 4, v244
	s_lshl_b32 s1, s8, 12
	s_add_u32 s13, s1, 0xfff
	s_cmp_eq_u32 s12, 0
	s_cselect_b64 s[18:19], -1, 0
	v_mov_b32_e32 v242, 0x1c00
	v_and_b32_e32 v241, 3, v244
	v_and_b32_e32 v240, 3, v243
	v_xor_b32_e32 v241, v241, v240
	v_lshlrev_b32_e32 v241, 4, v241
	v_add_u32_e32 v240, 0, v245
	v_add_u32_e32 v239, s1, v240
	v_sub_u32_e32 v240, s13, v240
	v_cndmask_b32_e64 v239, v240, v239, s[18:19]
	v_mul_lo_u32 v239, v239, v242
	v_add_u32_e32 v228, v239, v241
	v_add_u32_e32 v240, 16, v245
	v_add_u32_e32 v239, s1, v240
	v_sub_u32_e32 v240, s13, v240
	v_cndmask_b32_e64 v239, v240, v239, s[18:19]
	v_mul_lo_u32 v239, v239, v242
	v_add_u32_e32 v230, v239, v241
	v_add_u32_e32 v240, 32, v245
	v_add_u32_e32 v239, s1, v240
	v_sub_u32_e32 v240, s13, v240
	v_cndmask_b32_e64 v239, v240, v239, s[18:19]
	v_mul_lo_u32 v239, v239, v242
	v_add_u32_e32 v231, v239, v241
	v_add_u32_e32 v240, 48, v245
	v_add_u32_e32 v239, s1, v240
	v_sub_u32_e32 v240, s13, v240
	v_cndmask_b32_e64 v239, v240, v239, s[18:19]
	v_mul_lo_u32 v239, v239, v242
	v_add_u32_e32 v232, v239, v241
	s_lshl_b32 s17, s0, 4
	v_add_u32_e32 v240, 0, v243
	v_add_u32_e32 v240, s17, v240
	v_add_u32_e32 v239, s1, v240
	v_sub_u32_e32 v240, s13, v240
	v_cndmask_b32_e64 v239, v240, v239, s[18:19]
	v_mul_lo_u32 v239, v239, v242
	v_lshl_or_b32 v240, v243, 2, 0
	v_and_b32_e32 v238, 15, v244
	v_xor_b32_e32 v240, v240, v238
	v_lshl_add_u32 v252, v240, 4, v239
	v_add_u32_e32 v240, 4, v243
	v_add_u32_e32 v240, s17, v240
	v_add_u32_e32 v239, s1, v240
	v_sub_u32_e32 v240, s13, v240
	v_cndmask_b32_e64 v239, v240, v239, s[18:19]
	v_mul_lo_u32 v239, v239, v242
	v_lshl_or_b32 v240, v243, 2, 1
	v_and_b32_e32 v238, 15, v244
	v_xor_b32_e32 v240, v240, v238
	v_lshl_add_u32 v253, v240, 4, v239
	v_add_u32_e32 v240, 8, v243
	v_add_u32_e32 v240, s17, v240
	v_add_u32_e32 v239, s1, v240
	v_sub_u32_e32 v240, s13, v240
	v_cndmask_b32_e64 v239, v240, v239, s[18:19]
	v_mul_lo_u32 v239, v239, v242
	v_lshl_or_b32 v240, v243, 2, 2
	v_and_b32_e32 v238, 15, v244
	v_xor_b32_e32 v240, v240, v238
	v_lshl_add_u32 v254, v240, 4, v239
	v_add_u32_e32 v240, 12, v243
	v_add_u32_e32 v240, s17, v240
	v_add_u32_e32 v239, s1, v240
	v_sub_u32_e32 v240, s13, v240
	v_cndmask_b32_e64 v239, v240, v239, s[18:19]
	v_mul_lo_u32 v239, v239, v242
	v_lshl_or_b32 v240, v243, 2, 3
	v_and_b32_e32 v238, 15, v244
	v_xor_b32_e32 v240, v240, v238
	v_lshl_add_u32 v255, v240, 4, v239
	s_mov_b32 s33, 0x70000
	s_sub_u32 s13, 0, s33
	s_cmp_eq_u32 s12, 0
	s_cselect_b32 s33, s33, s13
	s_lshl_b32 s13, s9, 8
	s_add_u32 s34, s92, s13
	s_addc_u32 s35, s93, 0
	s_lshl_b32 s1, s0, 6
	s_add_u32 s30, s34, s1
	s_addc_u32 s31, s35, 0
	s_add_u32 s34, s34, 0xc00
	s_addc_u32 s35, s35, 0
	s_movk_i32 s1, 0x800
	s_cmp_eq_u32 s12, 0
	s_cselect_b32 s1, 0x400, s1
	s_add_u32 s14, s30, s1
	s_addc_u32 s15, s31, 0
	v_and_b32_e32 v241, 3, v244
	v_xor_b32_e32 v241, s0, v241
	v_lshlrev_b32_e32 v241, 6, v241
	v_lshl_add_u32 v241, v244, 8, v241
	v_bfe_u32 v240, v244, 2, 2
	v_xor_b32_e32 v239, 0, v240
	v_lshl_add_u32 v222, v239, 4, v241
	v_xor_b32_e32 v239, 1, v240
	v_lshl_add_u32 v223, v239, 4, v241
	v_xor_b32_e32 v239, 2, v240
	v_lshl_add_u32 v224, v239, 4, v241
	v_xor_b32_e32 v239, 3, v240
	v_lshl_add_u32 v225, v239, 4, v241
	v_mov_b32_e32 v239, 0x110
	v_mul_lo_u32 v241, v244, v239
	s_lshl_b32 s1, s0, 6
	v_add_u32_e32 v241, s1, v241
	v_add_u32_e32 v226, 0x10400, v241
	v_add_u32_e32 v227, 0x14800, v241
	s_lshl_b32 s1, s0, 7
	v_mov_b32_e32 v247, s1
	s_lshl_b32 s71, s0, 13
	s_add_u32 s71, s71, 0x1b400
	s_lshl_b32 s72, s0, 12
	v_lshlrev_b32_e32 v241, 6, v244
	v_add_u32_e32 v241, s71, v241
	v_xor_b32_e32 v239, 0, v240
	v_lshl_add_u32 v248, v239, 4, v241
	v_xor_b32_e32 v239, 1, v240
	v_lshl_add_u32 v249, v239, 4, v241
	v_xor_b32_e32 v239, 2, v240
	v_lshl_add_u32 v250, v239, 4, v241
	v_xor_b32_e32 v239, 3, v240
	v_lshl_add_u32 v251, v239, 4, v241
	v_subrev_u32_e32 v228, s33, v228
	v_subrev_u32_e32 v230, s33, v230
	v_subrev_u32_e32 v231, s33, v231
	v_subrev_u32_e32 v232, s33, v232
	v_add_u32_e32 v228, s33, v228
	v_add_u32_e32 v230, s33, v230
	v_add_u32_e32 v231, s33, v231
	v_add_u32_e32 v232, s33, v232
	s_add_u32 m0, s71, 0
	s_nop 0
	global_load_lds_dwordx4 v228, s[14:15]
	s_add_u32 m0, s71, 4096
	s_nop 0
	global_load_lds_dwordx4 v228, s[30:31]
	s_add_u32 m0, s71, 1024
	s_nop 0
	global_load_lds_dwordx4 v230, s[14:15]
	s_add_u32 m0, s71, 5120
	s_nop 0
	global_load_lds_dwordx4 v230, s[30:31]
	s_add_u32 m0, s71, 2048
	s_nop 0
	global_load_lds_dwordx4 v231, s[14:15]
	s_add_u32 m0, s71, 6144
	s_nop 0
	global_load_lds_dwordx4 v231, s[30:31]
	s_add_u32 m0, s71, 3072
	s_nop 0
	global_load_lds_dwordx4 v232, s[14:15]
	s_add_u32 m0, s71, 7168
	s_nop 0
	global_load_lds_dwordx4 v232, s[30:31]
	s_mov_b32 s70, 0
.Lh2_prep_loop:
	s_add_u32 m0, s72, 33792
	s_nop 0
	global_load_lds_dwordx4 v252, s[34:35]
	s_add_u32 m0, s72, 34816
	s_nop 0
	global_load_lds_dwordx4 v253, s[34:35]
	s_add_u32 m0, s72, 35840
	s_nop 0
	global_load_lds_dwordx4 v254, s[34:35]
	s_add_u32 m0, s72, 36864
	s_nop 0
	global_load_lds_dwordx4 v255, s[34:35]
	v_add_u32_e32 v252, s33, v252
	v_add_u32_e32 v253, s33, v253
	v_add_u32_e32 v254, s33, v254
	v_add_u32_e32 v255, s33, v255
	s_waitcnt vmcnt(4)
	ds_read_b128 v[234:237], v248
	ds_read_b128 v[238:241], v249
	ds_read_b128 v[242:245], v250
	ds_read_b128 v[168:171], v251
	s_waitcnt lgkmcnt(0)
	v_lshlrev_b32_e32 v96, 16, v234
	v_and_b32_e32 v97, 0xffff0000, v234
	v_lshlrev_b32_e32 v98, 16, v235
	v_and_b32_e32 v99, 0xffff0000, v235
	v_lshlrev_b32_e32 v100, 16, v236
	v_and_b32_e32 v101, 0xffff0000, v236
	v_lshlrev_b32_e32 v102, 16, v237
	v_and_b32_e32 v103, 0xffff0000, v237
	v_lshlrev_b32_e32 v104, 16, v238
	v_and_b32_e32 v105, 0xffff0000, v238
	v_lshlrev_b32_e32 v106, 16, v239
	v_and_b32_e32 v107, 0xffff0000, v239
	v_lshlrev_b32_e32 v108, 16, v240
	v_and_b32_e32 v109, 0xffff0000, v240
	v_lshlrev_b32_e32 v110, 16, v241
	v_and_b32_e32 v111, 0xffff0000, v241
	v_lshlrev_b32_e32 v112, 16, v242
	v_and_b32_e32 v113, 0xffff0000, v242
	v_lshlrev_b32_e32 v114, 16, v243
	v_and_b32_e32 v115, 0xffff0000, v243
	v_lshlrev_b32_e32 v116, 16, v244
	v_and_b32_e32 v117, 0xffff0000, v244
	v_lshlrev_b32_e32 v118, 16, v245
	v_and_b32_e32 v119, 0xffff0000, v245
	v_lshlrev_b32_e32 v120, 16, v168
	v_and_b32_e32 v121, 0xffff0000, v168
	v_lshlrev_b32_e32 v122, 16, v169
	v_and_b32_e32 v123, 0xffff0000, v169
	v_lshlrev_b32_e32 v124, 16, v170
	v_and_b32_e32 v125, 0xffff0000, v170
	v_lshlrev_b32_e32 v126, 16, v171
	v_and_b32_e32 v127, 0xffff0000, v171
	ds_read_b128 v[234:237], v248 offset:4096
	ds_read_b128 v[238:241], v249 offset:4096
	ds_read_b128 v[242:245], v250 offset:4096
	ds_read_b128 v[168:171], v251 offset:4096
	v_sub_f32_e32 v128, 1.0, v96
	v_sub_f32_e32 v129, 1.0, v97
	v_sub_f32_e32 v130, 1.0, v98
	v_sub_f32_e32 v131, 1.0, v99
	v_sub_f32_e32 v132, 1.0, v100
	v_sub_f32_e32 v133, 1.0, v101
	v_sub_f32_e32 v134, 1.0, v102
	v_sub_f32_e32 v135, 1.0, v103
	v_sub_f32_e32 v136, 1.0, v104
	v_sub_f32_e32 v137, 1.0, v105
	v_sub_f32_e32 v138, 1.0, v106
	v_sub_f32_e32 v139, 1.0, v107
	v_sub_f32_e32 v140, 1.0, v108
	v_sub_f32_e32 v141, 1.0, v109
	v_sub_f32_e32 v142, 1.0, v110
	v_sub_f32_e32 v143, 1.0, v111
	v_sub_f32_e32 v144, 1.0, v112
	v_sub_f32_e32 v145, 1.0, v113
	v_sub_f32_e32 v146, 1.0, v114
	v_sub_f32_e32 v147, 1.0, v115
	v_sub_f32_e32 v148, 1.0, v116
	v_sub_f32_e32 v149, 1.0, v117
	v_sub_f32_e32 v150, 1.0, v118
	v_sub_f32_e32 v151, 1.0, v119
	v_sub_f32_e32 v152, 1.0, v120
	v_sub_f32_e32 v153, 1.0, v121
	v_sub_f32_e32 v154, 1.0, v122
	v_sub_f32_e32 v155, 1.0, v123
	v_sub_f32_e32 v156, 1.0, v124
	v_sub_f32_e32 v157, 1.0, v125
	v_sub_f32_e32 v158, 1.0, v126
	v_sub_f32_e32 v159, 1.0, v127
	v_mul_f32_dpp v128, v128, v128 row_shr:1 row_mask:0xf bank_mask:0xf
	v_mul_f32_dpp v129, v129, v129 row_shr:1 row_mask:0xf bank_mask:0xf
	v_mul_f32_dpp v130, v130, v130 row_shr:1 row_mask:0xf bank_mask:0xf
	v_mul_f32_dpp v131, v131, v131 row_shr:1 row_mask:0xf bank_mask:0xf
	v_mul_f32_dpp v132, v132, v132 row_shr:1 row_mask:0xf bank_mask:0xf
	v_mul_f32_dpp v133, v133, v133 row_shr:1 row_mask:0xf bank_mask:0xf
	v_mul_f32_dpp v134, v134, v134 row_shr:1 row_mask:0xf bank_mask:0xf
	v_mul_f32_dpp v135, v135, v135 row_shr:1 row_mask:0xf bank_mask:0xf
	v_mul_f32_dpp v136, v136, v136 row_shr:1 row_mask:0xf bank_mask:0xf
	v_mul_f32_dpp v137, v137, v137 row_shr:1 row_mask:0xf bank_mask:0xf
	v_mul_f32_dpp v138, v138, v138 row_shr:1 row_mask:0xf bank_mask:0xf
	v_mul_f32_dpp v139, v139, v139 row_shr:1 row_mask:0xf bank_mask:0xf
	v_mul_f32_dpp v140, v140, v140 row_shr:1 row_mask:0xf bank_mask:0xf
	v_mul_f32_dpp v141, v141, v141 row_shr:1 row_mask:0xf bank_mask:0xf
	v_mul_f32_dpp v142, v142, v142 row_shr:1 row_mask:0xf bank_mask:0xf
	v_mul_f32_dpp v143, v143, v143 row_shr:1 row_mask:0xf bank_mask:0xf
	v_mul_f32_dpp v144, v144, v144 row_shr:1 row_mask:0xf bank_mask:0xf
	v_mul_f32_dpp v145, v145, v145 row_shr:1 row_mask:0xf bank_mask:0xf
	v_mul_f32_dpp v146, v146, v146 row_shr:1 row_mask:0xf bank_mask:0xf
	v_mul_f32_dpp v147, v147, v147 row_shr:1 row_mask:0xf bank_mask:0xf
	v_mul_f32_dpp v148, v148, v148 row_shr:1 row_mask:0xf bank_mask:0xf
	v_mul_f32_dpp v149, v149, v149 row_shr:1 row_mask:0xf bank_mask:0xf
	v_mul_f32_dpp v150, v150, v150 row_shr:1 row_mask:0xf bank_mask:0xf
	v_mul_f32_dpp v151, v151, v151 row_shr:1 row_mask:0xf bank_mask:0xf
	v_mul_f32_dpp v152, v152, v152 row_shr:1 row_mask:0xf bank_mask:0xf
	v_mul_f32_dpp v153, v153, v153 row_shr:1 row_mask:0xf bank_mask:0xf
	v_mul_f32_dpp v154, v154, v154 row_shr:1 row_mask:0xf bank_mask:0xf
	v_mul_f32_dpp v155, v155, v155 row_shr:1 row_mask:0xf bank_mask:0xf
	v_mul_f32_dpp v156, v156, v156 row_shr:1 row_mask:0xf bank_mask:0xf
	v_mul_f32_dpp v157, v157, v157 row_shr:1 row_mask:0xf bank_mask:0xf
	v_mul_f32_dpp v158, v158, v158 row_shr:1 row_mask:0xf bank_mask:0xf
	v_mul_f32_dpp v159, v159, v159 row_shr:1 row_mask:0xf bank_mask:0xf
	v_mul_f32_dpp v128, v128, v128 row_shr:2 row_mask:0xf bank_mask:0xf
	v_mul_f32_dpp v129, v129, v129 row_shr:2 row_mask:0xf bank_mask:0xf
	v_mul_f32_dpp v130, v130, v130 row_shr:2 row_mask:0xf bank_mask:0xf
	v_mul_f32_dpp v131, v131, v131 row_shr:2 row_mask:0xf bank_mask:0xf
	v_mul_f32_dpp v132, v132, v132 row_shr:2 row_mask:0xf bank_mask:0xf
	v_mul_f32_dpp v133, v133, v133 row_shr:2 row_mask:0xf bank_mask:0xf
	v_mul_f32_dpp v134, v134, v134 row_shr:2 row_mask:0xf bank_mask:0xf
	v_mul_f32_dpp v135, v135, v135 row_shr:2 row_mask:0xf bank_mask:0xf
	v_mul_f32_dpp v136, v136, v136 row_shr:2 row_mask:0xf bank_mask:0xf
	v_mul_f32_dpp v137, v137, v137 row_shr:2 row_mask:0xf bank_mask:0xf
	v_mul_f32_dpp v138, v138, v138 row_shr:2 row_mask:0xf bank_mask:0xf
	v_mul_f32_dpp v139, v139, v139 row_shr:2 row_mask:0xf bank_mask:0xf
	v_mul_f32_dpp v140, v140, v140 row_shr:2 row_mask:0xf bank_mask:0xf
	v_mul_f32_dpp v141, v141, v141 row_shr:2 row_mask:0xf bank_mask:0xf
	v_mul_f32_dpp v142, v142, v142 row_shr:2 row_mask:0xf bank_mask:0xf
	v_mul_f32_dpp v143, v143, v143 row_shr:2 row_mask:0xf bank_mask:0xf
	v_mul_f32_dpp v144, v144, v144 row_shr:2 row_mask:0xf bank_mask:0xf
	v_mul_f32_dpp v145, v145, v145 row_shr:2 row_mask:0xf bank_mask:0xf
	v_mul_f32_dpp v146, v146, v146 row_shr:2 row_mask:0xf bank_mask:0xf
	v_mul_f32_dpp v147, v147, v147 row_shr:2 row_mask:0xf bank_mask:0xf
	v_mul_f32_dpp v148, v148, v148 row_shr:2 row_mask:0xf bank_mask:0xf
	v_mul_f32_dpp v149, v149, v149 row_shr:2 row_mask:0xf bank_mask:0xf
	v_mul_f32_dpp v150, v150, v150 row_shr:2 row_mask:0xf bank_mask:0xf
	v_mul_f32_dpp v151, v151, v151 row_shr:2 row_mask:0xf bank_mask:0xf
	v_mul_f32_dpp v152, v152, v152 row_shr:2 row_mask:0xf bank_mask:0xf
	v_mul_f32_dpp v153, v153, v153 row_shr:2 row_mask:0xf bank_mask:0xf
	v_mul_f32_dpp v154, v154, v154 row_shr:2 row_mask:0xf bank_mask:0xf
	v_mul_f32_dpp v155, v155, v155 row_shr:2 row_mask:0xf bank_mask:0xf
	v_mul_f32_dpp v156, v156, v156 row_shr:2 row_mask:0xf bank_mask:0xf
	v_mul_f32_dpp v157, v157, v157 row_shr:2 row_mask:0xf bank_mask:0xf
	v_mul_f32_dpp v158, v158, v158 row_shr:2 row_mask:0xf bank_mask:0xf
	v_mul_f32_dpp v159, v159, v159 row_shr:2 row_mask:0xf bank_mask:0xf
	v_mul_f32_dpp v128, v128, v128 row_shr:4 row_mask:0xf bank_mask:0xf
	v_mul_f32_dpp v129, v129, v129 row_shr:4 row_mask:0xf bank_mask:0xf
	v_mul_f32_dpp v130, v130, v130 row_shr:4 row_mask:0xf bank_mask:0xf
	v_mul_f32_dpp v131, v131, v131 row_shr:4 row_mask:0xf bank_mask:0xf
	v_mul_f32_dpp v132, v132, v132 row_shr:4 row_mask:0xf bank_mask:0xf
	v_mul_f32_dpp v133, v133, v133 row_shr:4 row_mask:0xf bank_mask:0xf
	v_mul_f32_dpp v134, v134, v134 row_shr:4 row_mask:0xf bank_mask:0xf
	v_mul_f32_dpp v135, v135, v135 row_shr:4 row_mask:0xf bank_mask:0xf
	v_mul_f32_dpp v136, v136, v136 row_shr:4 row_mask:0xf bank_mask:0xf
	v_mul_f32_dpp v137, v137, v137 row_shr:4 row_mask:0xf bank_mask:0xf
	v_mul_f32_dpp v138, v138, v138 row_shr:4 row_mask:0xf bank_mask:0xf
	v_mul_f32_dpp v139, v139, v139 row_shr:4 row_mask:0xf bank_mask:0xf
	v_mul_f32_dpp v140, v140, v140 row_shr:4 row_mask:0xf bank_mask:0xf
	v_mul_f32_dpp v141, v141, v141 row_shr:4 row_mask:0xf bank_mask:0xf
	v_mul_f32_dpp v142, v142, v142 row_shr:4 row_mask:0xf bank_mask:0xf
	v_mul_f32_dpp v143, v143, v143 row_shr:4 row_mask:0xf bank_mask:0xf
	v_mul_f32_dpp v144, v144, v144 row_shr:4 row_mask:0xf bank_mask:0xf
	v_mul_f32_dpp v145, v145, v145 row_shr:4 row_mask:0xf bank_mask:0xf
	v_mul_f32_dpp v146, v146, v146 row_shr:4 row_mask:0xf bank_mask:0xf
	v_mul_f32_dpp v147, v147, v147 row_shr:4 row_mask:0xf bank_mask:0xf
	v_mul_f32_dpp v148, v148, v148 row_shr:4 row_mask:0xf bank_mask:0xf
	v_mul_f32_dpp v149, v149, v149 row_shr:4 row_mask:0xf bank_mask:0xf
	v_mul_f32_dpp v150, v150, v150 row_shr:4 row_mask:0xf bank_mask:0xf
	v_mul_f32_dpp v151, v151, v151 row_shr:4 row_mask:0xf bank_mask:0xf
	v_mul_f32_dpp v152, v152, v152 row_shr:4 row_mask:0xf bank_mask:0xf
	v_mul_f32_dpp v153, v153, v153 row_shr:4 row_mask:0xf bank_mask:0xf
	v_mul_f32_dpp v154, v154, v154 row_shr:4 row_mask:0xf bank_mask:0xf
	v_mul_f32_dpp v155, v155, v155 row_shr:4 row_mask:0xf bank_mask:0xf
	v_mul_f32_dpp v156, v156, v156 row_shr:4 row_mask:0xf bank_mask:0xf
	v_mul_f32_dpp v157, v157, v157 row_shr:4 row_mask:0xf bank_mask:0xf
	v_mul_f32_dpp v158, v158, v158 row_shr:4 row_mask:0xf bank_mask:0xf
	v_mul_f32_dpp v159, v159, v159 row_shr:4 row_mask:0xf bank_mask:0xf
	v_mul_f32_dpp v128, v128, v128 row_shr:8 row_mask:0xf bank_mask:0xf
	v_mul_f32_dpp v129, v129, v129 row_shr:8 row_mask:0xf bank_mask:0xf
	v_mul_f32_dpp v130, v130, v130 row_shr:8 row_mask:0xf bank_mask:0xf
	v_mul_f32_dpp v131, v131, v131 row_shr:8 row_mask:0xf bank_mask:0xf
	v_mul_f32_dpp v132, v132, v132 row_shr:8 row_mask:0xf bank_mask:0xf
	v_mul_f32_dpp v133, v133, v133 row_shr:8 row_mask:0xf bank_mask:0xf
	v_mul_f32_dpp v134, v134, v134 row_shr:8 row_mask:0xf bank_mask:0xf
	v_mul_f32_dpp v135, v135, v135 row_shr:8 row_mask:0xf bank_mask:0xf
	v_mul_f32_dpp v136, v136, v136 row_shr:8 row_mask:0xf bank_mask:0xf
	v_mul_f32_dpp v137, v137, v137 row_shr:8 row_mask:0xf bank_mask:0xf
	v_mul_f32_dpp v138, v138, v138 row_shr:8 row_mask:0xf bank_mask:0xf
	v_mul_f32_dpp v139, v139, v139 row_shr:8 row_mask:0xf bank_mask:0xf
	v_mul_f32_dpp v140, v140, v140 row_shr:8 row_mask:0xf bank_mask:0xf
	v_mul_f32_dpp v141, v141, v141 row_shr:8 row_mask:0xf bank_mask:0xf
	v_mul_f32_dpp v142, v142, v142 row_shr:8 row_mask:0xf bank_mask:0xf
	v_mul_f32_dpp v143, v143, v143 row_shr:8 row_mask:0xf bank_mask:0xf
	v_mul_f32_dpp v144, v144, v144 row_shr:8 row_mask:0xf bank_mask:0xf
	v_mul_f32_dpp v145, v145, v145 row_shr:8 row_mask:0xf bank_mask:0xf
	v_mul_f32_dpp v146, v146, v146 row_shr:8 row_mask:0xf bank_mask:0xf
	v_mul_f32_dpp v147, v147, v147 row_shr:8 row_mask:0xf bank_mask:0xf
	v_mul_f32_dpp v148, v148, v148 row_shr:8 row_mask:0xf bank_mask:0xf
	v_mul_f32_dpp v149, v149, v149 row_shr:8 row_mask:0xf bank_mask:0xf
	v_mul_f32_dpp v150, v150, v150 row_shr:8 row_mask:0xf bank_mask:0xf
	v_mul_f32_dpp v151, v151, v151 row_shr:8 row_mask:0xf bank_mask:0xf
	v_mul_f32_dpp v152, v152, v152 row_shr:8 row_mask:0xf bank_mask:0xf
	v_mul_f32_dpp v153, v153, v153 row_shr:8 row_mask:0xf bank_mask:0xf
	v_mul_f32_dpp v154, v154, v154 row_shr:8 row_mask:0xf bank_mask:0xf
	v_mul_f32_dpp v155, v155, v155 row_shr:8 row_mask:0xf bank_mask:0xf
	v_mul_f32_dpp v156, v156, v156 row_shr:8 row_mask:0xf bank_mask:0xf
	v_mul_f32_dpp v157, v157, v157 row_shr:8 row_mask:0xf bank_mask:0xf
	v_mul_f32_dpp v158, v158, v158 row_shr:8 row_mask:0xf bank_mask:0xf
	v_mul_f32_dpp v159, v159, v159 row_shr:8 row_mask:0xf bank_mask:0xf
	v_mul_f32_dpp v128, v128, v128 row_bcast:15 row_mask:0xa bank_mask:0xf
	v_mul_f32_dpp v129, v129, v129 row_bcast:15 row_mask:0xa bank_mask:0xf
	v_mul_f32_dpp v130, v130, v130 row_bcast:15 row_mask:0xa bank_mask:0xf
	v_mul_f32_dpp v131, v131, v131 row_bcast:15 row_mask:0xa bank_mask:0xf
	v_mul_f32_dpp v132, v132, v132 row_bcast:15 row_mask:0xa bank_mask:0xf
	v_mul_f32_dpp v133, v133, v133 row_bcast:15 row_mask:0xa bank_mask:0xf
	v_mul_f32_dpp v134, v134, v134 row_bcast:15 row_mask:0xa bank_mask:0xf
	v_mul_f32_dpp v135, v135, v135 row_bcast:15 row_mask:0xa bank_mask:0xf
	v_mul_f32_dpp v136, v136, v136 row_bcast:15 row_mask:0xa bank_mask:0xf
	v_mul_f32_dpp v137, v137, v137 row_bcast:15 row_mask:0xa bank_mask:0xf
	v_mul_f32_dpp v138, v138, v138 row_bcast:15 row_mask:0xa bank_mask:0xf
	v_mul_f32_dpp v139, v139, v139 row_bcast:15 row_mask:0xa bank_mask:0xf
	v_mul_f32_dpp v140, v140, v140 row_bcast:15 row_mask:0xa bank_mask:0xf
	v_mul_f32_dpp v141, v141, v141 row_bcast:15 row_mask:0xa bank_mask:0xf
	v_mul_f32_dpp v142, v142, v142 row_bcast:15 row_mask:0xa bank_mask:0xf
	v_mul_f32_dpp v143, v143, v143 row_bcast:15 row_mask:0xa bank_mask:0xf
	v_mul_f32_dpp v144, v144, v144 row_bcast:15 row_mask:0xa bank_mask:0xf
	v_mul_f32_dpp v145, v145, v145 row_bcast:15 row_mask:0xa bank_mask:0xf
	v_mul_f32_dpp v146, v146, v146 row_bcast:15 row_mask:0xa bank_mask:0xf
	v_mul_f32_dpp v147, v147, v147 row_bcast:15 row_mask:0xa bank_mask:0xf
	v_mul_f32_dpp v148, v148, v148 row_bcast:15 row_mask:0xa bank_mask:0xf
	v_mul_f32_dpp v149, v149, v149 row_bcast:15 row_mask:0xa bank_mask:0xf
	v_mul_f32_dpp v150, v150, v150 row_bcast:15 row_mask:0xa bank_mask:0xf
	v_mul_f32_dpp v151, v151, v151 row_bcast:15 row_mask:0xa bank_mask:0xf
	v_mul_f32_dpp v152, v152, v152 row_bcast:15 row_mask:0xa bank_mask:0xf
	v_mul_f32_dpp v153, v153, v153 row_bcast:15 row_mask:0xa bank_mask:0xf
	v_mul_f32_dpp v154, v154, v154 row_bcast:15 row_mask:0xa bank_mask:0xf
	v_mul_f32_dpp v155, v155, v155 row_bcast:15 row_mask:0xa bank_mask:0xf
	v_mul_f32_dpp v156, v156, v156 row_bcast:15 row_mask:0xa bank_mask:0xf
	v_mul_f32_dpp v157, v157, v157 row_bcast:15 row_mask:0xa bank_mask:0xf
	v_mul_f32_dpp v158, v158, v158 row_bcast:15 row_mask:0xa bank_mask:0xf
	v_mul_f32_dpp v159, v159, v159 row_bcast:15 row_mask:0xa bank_mask:0xf
	v_mul_f32_dpp v128, v128, v128 row_bcast:31 row_mask:0xc bank_mask:0xf
	v_mul_f32_dpp v129, v129, v129 row_bcast:31 row_mask:0xc bank_mask:0xf
	v_mul_f32_dpp v130, v130, v130 row_bcast:31 row_mask:0xc bank_mask:0xf
	v_mul_f32_dpp v131, v131, v131 row_bcast:31 row_mask:0xc bank_mask:0xf
	v_mul_f32_dpp v132, v132, v132 row_bcast:31 row_mask:0xc bank_mask:0xf
	v_mul_f32_dpp v133, v133, v133 row_bcast:31 row_mask:0xc bank_mask:0xf
	v_mul_f32_dpp v134, v134, v134 row_bcast:31 row_mask:0xc bank_mask:0xf
	v_mul_f32_dpp v135, v135, v135 row_bcast:31 row_mask:0xc bank_mask:0xf
	v_mul_f32_dpp v136, v136, v136 row_bcast:31 row_mask:0xc bank_mask:0xf
	v_mul_f32_dpp v137, v137, v137 row_bcast:31 row_mask:0xc bank_mask:0xf
	v_mul_f32_dpp v138, v138, v138 row_bcast:31 row_mask:0xc bank_mask:0xf
	v_mul_f32_dpp v139, v139, v139 row_bcast:31 row_mask:0xc bank_mask:0xf
	v_mul_f32_dpp v140, v140, v140 row_bcast:31 row_mask:0xc bank_mask:0xf
	v_mul_f32_dpp v141, v141, v141 row_bcast:31 row_mask:0xc bank_mask:0xf
	v_mul_f32_dpp v142, v142, v142 row_bcast:31 row_mask:0xc bank_mask:0xf
	v_mul_f32_dpp v143, v143, v143 row_bcast:31 row_mask:0xc bank_mask:0xf
	v_mul_f32_dpp v144, v144, v144 row_bcast:31 row_mask:0xc bank_mask:0xf
	v_mul_f32_dpp v145, v145, v145 row_bcast:31 row_mask:0xc bank_mask:0xf
	v_mul_f32_dpp v146, v146, v146 row_bcast:31 row_mask:0xc bank_mask:0xf
	v_mul_f32_dpp v147, v147, v147 row_bcast:31 row_mask:0xc bank_mask:0xf
	v_mul_f32_dpp v148, v148, v148 row_bcast:31 row_mask:0xc bank_mask:0xf
	v_mul_f32_dpp v149, v149, v149 row_bcast:31 row_mask:0xc bank_mask:0xf
	v_mul_f32_dpp v150, v150, v150 row_bcast:31 row_mask:0xc bank_mask:0xf
	v_mul_f32_dpp v151, v151, v151 row_bcast:31 row_mask:0xc bank_mask:0xf
	v_mul_f32_dpp v152, v152, v152 row_bcast:31 row_mask:0xc bank_mask:0xf
	v_mul_f32_dpp v153, v153, v153 row_bcast:31 row_mask:0xc bank_mask:0xf
	v_mul_f32_dpp v154, v154, v154 row_bcast:31 row_mask:0xc bank_mask:0xf
	v_mul_f32_dpp v155, v155, v155 row_bcast:31 row_mask:0xc bank_mask:0xf
	v_mul_f32_dpp v156, v156, v156 row_bcast:31 row_mask:0xc bank_mask:0xf
	v_mul_f32_dpp v157, v157, v157 row_bcast:31 row_mask:0xc bank_mask:0xf
	v_mul_f32_dpp v158, v158, v158 row_bcast:31 row_mask:0xc bank_mask:0xf
	v_mul_f32_dpp v159, v159, v159 row_bcast:31 row_mask:0xc bank_mask:0xf
	s_waitcnt lgkmcnt(0)
	v_add_u32_e32 v228, s33, v228
	v_add_u32_e32 v230, s33, v230
	v_add_u32_e32 v231, s33, v231
	v_add_u32_e32 v232, s33, v232
	s_add_u32 m0, s71, 0
	s_nop 0
	global_load_lds_dwordx4 v228, s[14:15]
	s_add_u32 m0, s71, 4096
	s_nop 0
	global_load_lds_dwordx4 v228, s[30:31]
	s_add_u32 m0, s71, 1024
	s_nop 0
	global_load_lds_dwordx4 v230, s[14:15]
	s_add_u32 m0, s71, 5120
	s_nop 0
	global_load_lds_dwordx4 v230, s[30:31]
	s_add_u32 m0, s71, 2048
	s_nop 0
	global_load_lds_dwordx4 v231, s[14:15]
	s_add_u32 m0, s71, 6144
	s_nop 0
	global_load_lds_dwordx4 v231, s[30:31]
	s_add_u32 m0, s71, 3072
	s_nop 0
	global_load_lds_dwordx4 v232, s[14:15]
	s_add_u32 m0, s71, 7168
	s_nop 0
	global_load_lds_dwordx4 v232, s[30:31]
	s_mov_b32 exec_lo, 0
	s_brev_b32 exec_hi, 1
	ds_write_b128 v247, v[128:131] offset:0
	ds_write_b128 v247, v[132:135] offset:16
	ds_write_b128 v247, v[136:139] offset:32
	ds_write_b128 v247, v[140:143] offset:48
	ds_write_b128 v247, v[144:147] offset:64
	ds_write_b128 v247, v[148:151] offset:80
	ds_write_b128 v247, v[152:155] offset:96
	ds_write_b128 v247, v[156:159] offset:112
	s_mov_b64 exec, -1
	v_rcp_f32_e32 v220, v128
	v_rcp_f32_e32 v221, v129
	v_lshlrev_b32_e32 v218, 16, v234
	v_and_b32_e32 v219, 0xffff0000, v234
	v_pk_mul_f32 v[218:219], v[128:129], v[218:219]
	v_pk_mul_f32 v[220:221], v[220:221], v[96:97]
	v_cvt_pk_bf16_f32 v202, v218, v219
	v_cvt_pk_bf16_f32 v184, v220, v221
	v_rcp_f32_e32 v220, v130
	v_rcp_f32_e32 v221, v131
	v_lshlrev_b32_e32 v218, 16, v235
	v_and_b32_e32 v219, 0xffff0000, v235
	v_pk_mul_f32 v[218:219], v[130:131], v[218:219]
	v_pk_mul_f32 v[220:221], v[220:221], v[98:99]
	v_cvt_pk_bf16_f32 v203, v218, v219
	v_cvt_pk_bf16_f32 v185, v220, v221
	v_rcp_f32_e32 v220, v132
	v_rcp_f32_e32 v221, v133
	v_lshlrev_b32_e32 v218, 16, v236
	v_and_b32_e32 v219, 0xffff0000, v236
	v_pk_mul_f32 v[218:219], v[132:133], v[218:219]
	v_pk_mul_f32 v[220:221], v[220:221], v[100:101]
	v_cvt_pk_bf16_f32 v204, v218, v219
	v_cvt_pk_bf16_f32 v186, v220, v221
	v_rcp_f32_e32 v220, v134
	v_rcp_f32_e32 v221, v135
	v_lshlrev_b32_e32 v218, 16, v237
	v_and_b32_e32 v219, 0xffff0000, v237
	v_pk_mul_f32 v[218:219], v[134:135], v[218:219]
	v_pk_mul_f32 v[220:221], v[220:221], v[102:103]
	v_cvt_pk_bf16_f32 v205, v218, v219
	v_cvt_pk_bf16_f32 v187, v220, v221
	v_rcp_f32_e32 v220, v136
	v_rcp_f32_e32 v221, v137
	v_lshlrev_b32_e32 v218, 16, v238
	v_and_b32_e32 v219, 0xffff0000, v238
	v_pk_mul_f32 v[218:219], v[136:137], v[218:219]
	v_pk_mul_f32 v[220:221], v[220:221], v[104:105]
	v_cvt_pk_bf16_f32 v206, v218, v219
	v_cvt_pk_bf16_f32 v188, v220, v221
	v_rcp_f32_e32 v220, v138
	v_rcp_f32_e32 v221, v139
	v_lshlrev_b32_e32 v218, 16, v239
	v_and_b32_e32 v219, 0xffff0000, v239
	v_pk_mul_f32 v[218:219], v[138:139], v[218:219]
	v_pk_mul_f32 v[220:221], v[220:221], v[106:107]
	v_cvt_pk_bf16_f32 v207, v218, v219
	v_cvt_pk_bf16_f32 v189, v220, v221
	v_rcp_f32_e32 v220, v140
	v_rcp_f32_e32 v221, v141
	v_lshlrev_b32_e32 v218, 16, v240
	v_and_b32_e32 v219, 0xffff0000, v240
	v_pk_mul_f32 v[218:219], v[140:141], v[218:219]
	v_pk_mul_f32 v[220:221], v[220:221], v[108:109]
	v_cvt_pk_bf16_f32 v208, v218, v219
	v_cvt_pk_bf16_f32 v190, v220, v221
	v_rcp_f32_e32 v220, v142
	v_rcp_f32_e32 v221, v143
	v_lshlrev_b32_e32 v218, 16, v241
	v_and_b32_e32 v219, 0xffff0000, v241
	v_pk_mul_f32 v[218:219], v[142:143], v[218:219]
	v_pk_mul_f32 v[220:221], v[220:221], v[110:111]
	v_cvt_pk_bf16_f32 v209, v218, v219
	v_cvt_pk_bf16_f32 v191, v220, v221
	v_rcp_f32_e32 v220, v144
	v_rcp_f32_e32 v221, v145
	v_lshlrev_b32_e32 v218, 16, v242
	v_and_b32_e32 v219, 0xffff0000, v242
	v_pk_mul_f32 v[218:219], v[144:145], v[218:219]
	v_pk_mul_f32 v[220:221], v[220:221], v[112:113]
	v_cvt_pk_bf16_f32 v210, v218, v219
	v_cvt_pk_bf16_f32 v192, v220, v221
	v_rcp_f32_e32 v220, v146
	v_rcp_f32_e32 v221, v147
	v_lshlrev_b32_e32 v218, 16, v243
	v_and_b32_e32 v219, 0xffff0000, v243
	v_pk_mul_f32 v[218:219], v[146:147], v[218:219]
	v_pk_mul_f32 v[220:221], v[220:221], v[114:115]
	v_cvt_pk_bf16_f32 v211, v218, v219
	v_cvt_pk_bf16_f32 v193, v220, v221
	v_rcp_f32_e32 v220, v148
	v_rcp_f32_e32 v221, v149
	v_lshlrev_b32_e32 v218, 16, v244
	v_and_b32_e32 v219, 0xffff0000, v244
	v_pk_mul_f32 v[218:219], v[148:149], v[218:219]
	v_pk_mul_f32 v[220:221], v[220:221], v[116:117]
	v_cvt_pk_bf16_f32 v212, v218, v219
	v_cvt_pk_bf16_f32 v194, v220, v221
	v_rcp_f32_e32 v220, v150
	v_rcp_f32_e32 v221, v151
	v_lshlrev_b32_e32 v218, 16, v245
	v_and_b32_e32 v219, 0xffff0000, v245
	v_pk_mul_f32 v[218:219], v[150:151], v[218:219]
	v_pk_mul_f32 v[220:221], v[220:221], v[118:119]
	v_cvt_pk_bf16_f32 v213, v218, v219
	v_cvt_pk_bf16_f32 v195, v220, v221
	v_rcp_f32_e32 v220, v152
	v_rcp_f32_e32 v221, v153
	v_lshlrev_b32_e32 v218, 16, v168
	v_and_b32_e32 v219, 0xffff0000, v168
	v_pk_mul_f32 v[218:219], v[152:153], v[218:219]
	v_pk_mul_f32 v[220:221], v[220:221], v[120:121]
	v_cvt_pk_bf16_f32 v214, v218, v219
	v_cvt_pk_bf16_f32 v196, v220, v221
	v_rcp_f32_e32 v220, v154
	v_rcp_f32_e32 v221, v155
	v_lshlrev_b32_e32 v218, 16, v169
	v_and_b32_e32 v219, 0xffff0000, v169
	v_pk_mul_f32 v[218:219], v[154:155], v[218:219]
	v_pk_mul_f32 v[220:221], v[220:221], v[122:123]
	v_cvt_pk_bf16_f32 v215, v218, v219
	v_cvt_pk_bf16_f32 v197, v220, v221
	v_rcp_f32_e32 v220, v156
	v_rcp_f32_e32 v221, v157
	v_lshlrev_b32_e32 v218, 16, v170
	v_and_b32_e32 v219, 0xffff0000, v170
	v_pk_mul_f32 v[218:219], v[156:157], v[218:219]
	v_pk_mul_f32 v[220:221], v[220:221], v[124:125]
	v_cvt_pk_bf16_f32 v216, v218, v219
	v_cvt_pk_bf16_f32 v198, v220, v221
	v_rcp_f32_e32 v220, v158
	v_rcp_f32_e32 v221, v159
	v_lshlrev_b32_e32 v218, 16, v171
	v_and_b32_e32 v219, 0xffff0000, v171
	v_pk_mul_f32 v[218:219], v[158:159], v[218:219]
	v_pk_mul_f32 v[220:221], v[220:221], v[126:127]
	v_cvt_pk_bf16_f32 v217, v218, v219
	v_cvt_pk_bf16_f32 v199, v220, v221
	ds_write_b128 v222, v[184:187] offset:1024
	ds_write_b128 v223, v[188:191] offset:1024
	ds_write_b128 v224, v[192:195] offset:1024
	ds_write_b128 v225, v[196:199] offset:1024
	ds_write_b128 v226, v[202:205]
	ds_write_b128 v226, v[206:209] offset:16
	ds_write_b128 v226, v[210:213] offset:32
	ds_write_b128 v226, v[214:217] offset:48
	s_waitcnt vmcnt(8)
	s_waitcnt lgkmcnt(0)
	s_barrier
	s_add_u32 m0, s72, 50176
	s_nop 0
	global_load_lds_dwordx4 v252, s[34:35]
	s_add_u32 m0, s72, 51200
	s_nop 0
	global_load_lds_dwordx4 v253, s[34:35]
	s_add_u32 m0, s72, 52224
	s_nop 0
	global_load_lds_dwordx4 v254, s[34:35]
	s_add_u32 m0, s72, 53248
	s_nop 0
	global_load_lds_dwordx4 v255, s[34:35]
	v_add_u32_e32 v252, s33, v252
	v_add_u32_e32 v253, s33, v253
	v_add_u32_e32 v254, s33, v254
	v_add_u32_e32 v255, s33, v255
	s_waitcnt vmcnt(4)
	ds_read_b128 v[234:237], v248
	ds_read_b128 v[238:241], v249
	ds_read_b128 v[242:245], v250
	ds_read_b128 v[168:171], v251
	s_waitcnt lgkmcnt(0)
	v_lshlrev_b32_e32 v96, 16, v234
	v_and_b32_e32 v97, 0xffff0000, v234
	v_lshlrev_b32_e32 v98, 16, v235
	v_and_b32_e32 v99, 0xffff0000, v235
	v_lshlrev_b32_e32 v100, 16, v236
	v_and_b32_e32 v101, 0xffff0000, v236
	v_lshlrev_b32_e32 v102, 16, v237
	v_and_b32_e32 v103, 0xffff0000, v237
	v_lshlrev_b32_e32 v104, 16, v238
	v_and_b32_e32 v105, 0xffff0000, v238
	v_lshlrev_b32_e32 v106, 16, v239
	v_and_b32_e32 v107, 0xffff0000, v239
	v_lshlrev_b32_e32 v108, 16, v240
	v_and_b32_e32 v109, 0xffff0000, v240
	v_lshlrev_b32_e32 v110, 16, v241
	v_and_b32_e32 v111, 0xffff0000, v241
	v_lshlrev_b32_e32 v112, 16, v242
	v_and_b32_e32 v113, 0xffff0000, v242
	v_lshlrev_b32_e32 v114, 16, v243
	v_and_b32_e32 v115, 0xffff0000, v243
	v_lshlrev_b32_e32 v116, 16, v244
	v_and_b32_e32 v117, 0xffff0000, v244
	v_lshlrev_b32_e32 v118, 16, v245
	v_and_b32_e32 v119, 0xffff0000, v245
	v_lshlrev_b32_e32 v120, 16, v168
	v_and_b32_e32 v121, 0xffff0000, v168
	v_lshlrev_b32_e32 v122, 16, v169
	v_and_b32_e32 v123, 0xffff0000, v169
	v_lshlrev_b32_e32 v124, 16, v170
	v_and_b32_e32 v125, 0xffff0000, v170
	v_lshlrev_b32_e32 v126, 16, v171
	v_and_b32_e32 v127, 0xffff0000, v171
	ds_read_b128 v[234:237], v248 offset:4096
	ds_read_b128 v[238:241], v249 offset:4096
	ds_read_b128 v[242:245], v250 offset:4096
	ds_read_b128 v[168:171], v251 offset:4096
	v_sub_f32_e32 v128, 1.0, v96
	v_sub_f32_e32 v129, 1.0, v97
	v_sub_f32_e32 v130, 1.0, v98
	v_sub_f32_e32 v131, 1.0, v99
	v_sub_f32_e32 v132, 1.0, v100
	v_sub_f32_e32 v133, 1.0, v101
	v_sub_f32_e32 v134, 1.0, v102
	v_sub_f32_e32 v135, 1.0, v103
	v_sub_f32_e32 v136, 1.0, v104
	v_sub_f32_e32 v137, 1.0, v105
	v_sub_f32_e32 v138, 1.0, v106
	v_sub_f32_e32 v139, 1.0, v107
	v_sub_f32_e32 v140, 1.0, v108
	v_sub_f32_e32 v141, 1.0, v109
	v_sub_f32_e32 v142, 1.0, v110
	v_sub_f32_e32 v143, 1.0, v111
	v_sub_f32_e32 v144, 1.0, v112
	v_sub_f32_e32 v145, 1.0, v113
	v_sub_f32_e32 v146, 1.0, v114
	v_sub_f32_e32 v147, 1.0, v115
	v_sub_f32_e32 v148, 1.0, v116
	v_sub_f32_e32 v149, 1.0, v117
	v_sub_f32_e32 v150, 1.0, v118
	v_sub_f32_e32 v151, 1.0, v119
	v_sub_f32_e32 v152, 1.0, v120
	v_sub_f32_e32 v153, 1.0, v121
	v_sub_f32_e32 v154, 1.0, v122
	v_sub_f32_e32 v155, 1.0, v123
	v_sub_f32_e32 v156, 1.0, v124
	v_sub_f32_e32 v157, 1.0, v125
	v_sub_f32_e32 v158, 1.0, v126
	v_sub_f32_e32 v159, 1.0, v127
	v_mul_f32_dpp v128, v128, v128 row_shr:1 row_mask:0xf bank_mask:0xf
	v_mul_f32_dpp v129, v129, v129 row_shr:1 row_mask:0xf bank_mask:0xf
	v_mul_f32_dpp v130, v130, v130 row_shr:1 row_mask:0xf bank_mask:0xf
	v_mul_f32_dpp v131, v131, v131 row_shr:1 row_mask:0xf bank_mask:0xf
	v_mul_f32_dpp v132, v132, v132 row_shr:1 row_mask:0xf bank_mask:0xf
	v_mul_f32_dpp v133, v133, v133 row_shr:1 row_mask:0xf bank_mask:0xf
	v_mul_f32_dpp v134, v134, v134 row_shr:1 row_mask:0xf bank_mask:0xf
	v_mul_f32_dpp v135, v135, v135 row_shr:1 row_mask:0xf bank_mask:0xf
	v_mul_f32_dpp v136, v136, v136 row_shr:1 row_mask:0xf bank_mask:0xf
	v_mul_f32_dpp v137, v137, v137 row_shr:1 row_mask:0xf bank_mask:0xf
	v_mul_f32_dpp v138, v138, v138 row_shr:1 row_mask:0xf bank_mask:0xf
	v_mul_f32_dpp v139, v139, v139 row_shr:1 row_mask:0xf bank_mask:0xf
	v_mul_f32_dpp v140, v140, v140 row_shr:1 row_mask:0xf bank_mask:0xf
	v_mul_f32_dpp v141, v141, v141 row_shr:1 row_mask:0xf bank_mask:0xf
	v_mul_f32_dpp v142, v142, v142 row_shr:1 row_mask:0xf bank_mask:0xf
	v_mul_f32_dpp v143, v143, v143 row_shr:1 row_mask:0xf bank_mask:0xf
	v_mul_f32_dpp v144, v144, v144 row_shr:1 row_mask:0xf bank_mask:0xf
	v_mul_f32_dpp v145, v145, v145 row_shr:1 row_mask:0xf bank_mask:0xf
	v_mul_f32_dpp v146, v146, v146 row_shr:1 row_mask:0xf bank_mask:0xf
	v_mul_f32_dpp v147, v147, v147 row_shr:1 row_mask:0xf bank_mask:0xf
	v_mul_f32_dpp v148, v148, v148 row_shr:1 row_mask:0xf bank_mask:0xf
	v_mul_f32_dpp v149, v149, v149 row_shr:1 row_mask:0xf bank_mask:0xf
	v_mul_f32_dpp v150, v150, v150 row_shr:1 row_mask:0xf bank_mask:0xf
	v_mul_f32_dpp v151, v151, v151 row_shr:1 row_mask:0xf bank_mask:0xf
	v_mul_f32_dpp v152, v152, v152 row_shr:1 row_mask:0xf bank_mask:0xf
	v_mul_f32_dpp v153, v153, v153 row_shr:1 row_mask:0xf bank_mask:0xf
	v_mul_f32_dpp v154, v154, v154 row_shr:1 row_mask:0xf bank_mask:0xf
	v_mul_f32_dpp v155, v155, v155 row_shr:1 row_mask:0xf bank_mask:0xf
	v_mul_f32_dpp v156, v156, v156 row_shr:1 row_mask:0xf bank_mask:0xf
	v_mul_f32_dpp v157, v157, v157 row_shr:1 row_mask:0xf bank_mask:0xf
	v_mul_f32_dpp v158, v158, v158 row_shr:1 row_mask:0xf bank_mask:0xf
	v_mul_f32_dpp v159, v159, v159 row_shr:1 row_mask:0xf bank_mask:0xf
	v_mul_f32_dpp v128, v128, v128 row_shr:2 row_mask:0xf bank_mask:0xf
	v_mul_f32_dpp v129, v129, v129 row_shr:2 row_mask:0xf bank_mask:0xf
	v_mul_f32_dpp v130, v130, v130 row_shr:2 row_mask:0xf bank_mask:0xf
	v_mul_f32_dpp v131, v131, v131 row_shr:2 row_mask:0xf bank_mask:0xf
	v_mul_f32_dpp v132, v132, v132 row_shr:2 row_mask:0xf bank_mask:0xf
	v_mul_f32_dpp v133, v133, v133 row_shr:2 row_mask:0xf bank_mask:0xf
	v_mul_f32_dpp v134, v134, v134 row_shr:2 row_mask:0xf bank_mask:0xf
	v_mul_f32_dpp v135, v135, v135 row_shr:2 row_mask:0xf bank_mask:0xf
	v_mul_f32_dpp v136, v136, v136 row_shr:2 row_mask:0xf bank_mask:0xf
	v_mul_f32_dpp v137, v137, v137 row_shr:2 row_mask:0xf bank_mask:0xf
	v_mul_f32_dpp v138, v138, v138 row_shr:2 row_mask:0xf bank_mask:0xf
	v_mul_f32_dpp v139, v139, v139 row_shr:2 row_mask:0xf bank_mask:0xf
	v_mul_f32_dpp v140, v140, v140 row_shr:2 row_mask:0xf bank_mask:0xf
	v_mul_f32_dpp v141, v141, v141 row_shr:2 row_mask:0xf bank_mask:0xf
	v_mul_f32_dpp v142, v142, v142 row_shr:2 row_mask:0xf bank_mask:0xf
	v_mul_f32_dpp v143, v143, v143 row_shr:2 row_mask:0xf bank_mask:0xf
	v_mul_f32_dpp v144, v144, v144 row_shr:2 row_mask:0xf bank_mask:0xf
	v_mul_f32_dpp v145, v145, v145 row_shr:2 row_mask:0xf bank_mask:0xf
	v_mul_f32_dpp v146, v146, v146 row_shr:2 row_mask:0xf bank_mask:0xf
	v_mul_f32_dpp v147, v147, v147 row_shr:2 row_mask:0xf bank_mask:0xf
	v_mul_f32_dpp v148, v148, v148 row_shr:2 row_mask:0xf bank_mask:0xf
	v_mul_f32_dpp v149, v149, v149 row_shr:2 row_mask:0xf bank_mask:0xf
	v_mul_f32_dpp v150, v150, v150 row_shr:2 row_mask:0xf bank_mask:0xf
	v_mul_f32_dpp v151, v151, v151 row_shr:2 row_mask:0xf bank_mask:0xf
	v_mul_f32_dpp v152, v152, v152 row_shr:2 row_mask:0xf bank_mask:0xf
	v_mul_f32_dpp v153, v153, v153 row_shr:2 row_mask:0xf bank_mask:0xf
	v_mul_f32_dpp v154, v154, v154 row_shr:2 row_mask:0xf bank_mask:0xf
	v_mul_f32_dpp v155, v155, v155 row_shr:2 row_mask:0xf bank_mask:0xf
	v_mul_f32_dpp v156, v156, v156 row_shr:2 row_mask:0xf bank_mask:0xf
	v_mul_f32_dpp v157, v157, v157 row_shr:2 row_mask:0xf bank_mask:0xf
	v_mul_f32_dpp v158, v158, v158 row_shr:2 row_mask:0xf bank_mask:0xf
	v_mul_f32_dpp v159, v159, v159 row_shr:2 row_mask:0xf bank_mask:0xf
	v_mul_f32_dpp v128, v128, v128 row_shr:4 row_mask:0xf bank_mask:0xf
	v_mul_f32_dpp v129, v129, v129 row_shr:4 row_mask:0xf bank_mask:0xf
	v_mul_f32_dpp v130, v130, v130 row_shr:4 row_mask:0xf bank_mask:0xf
	v_mul_f32_dpp v131, v131, v131 row_shr:4 row_mask:0xf bank_mask:0xf
	v_mul_f32_dpp v132, v132, v132 row_shr:4 row_mask:0xf bank_mask:0xf
	v_mul_f32_dpp v133, v133, v133 row_shr:4 row_mask:0xf bank_mask:0xf
	v_mul_f32_dpp v134, v134, v134 row_shr:4 row_mask:0xf bank_mask:0xf
	v_mul_f32_dpp v135, v135, v135 row_shr:4 row_mask:0xf bank_mask:0xf
	v_mul_f32_dpp v136, v136, v136 row_shr:4 row_mask:0xf bank_mask:0xf
	v_mul_f32_dpp v137, v137, v137 row_shr:4 row_mask:0xf bank_mask:0xf
	v_mul_f32_dpp v138, v138, v138 row_shr:4 row_mask:0xf bank_mask:0xf
	v_mul_f32_dpp v139, v139, v139 row_shr:4 row_mask:0xf bank_mask:0xf
	v_mul_f32_dpp v140, v140, v140 row_shr:4 row_mask:0xf bank_mask:0xf
	v_mul_f32_dpp v141, v141, v141 row_shr:4 row_mask:0xf bank_mask:0xf
	v_mul_f32_dpp v142, v142, v142 row_shr:4 row_mask:0xf bank_mask:0xf
	v_mul_f32_dpp v143, v143, v143 row_shr:4 row_mask:0xf bank_mask:0xf
	v_mul_f32_dpp v144, v144, v144 row_shr:4 row_mask:0xf bank_mask:0xf
	v_mul_f32_dpp v145, v145, v145 row_shr:4 row_mask:0xf bank_mask:0xf
	v_mul_f32_dpp v146, v146, v146 row_shr:4 row_mask:0xf bank_mask:0xf
	v_mul_f32_dpp v147, v147, v147 row_shr:4 row_mask:0xf bank_mask:0xf
	v_mul_f32_dpp v148, v148, v148 row_shr:4 row_mask:0xf bank_mask:0xf
	v_mul_f32_dpp v149, v149, v149 row_shr:4 row_mask:0xf bank_mask:0xf
	v_mul_f32_dpp v150, v150, v150 row_shr:4 row_mask:0xf bank_mask:0xf
	v_mul_f32_dpp v151, v151, v151 row_shr:4 row_mask:0xf bank_mask:0xf
	v_mul_f32_dpp v152, v152, v152 row_shr:4 row_mask:0xf bank_mask:0xf
	v_mul_f32_dpp v153, v153, v153 row_shr:4 row_mask:0xf bank_mask:0xf
	v_mul_f32_dpp v154, v154, v154 row_shr:4 row_mask:0xf bank_mask:0xf
	v_mul_f32_dpp v155, v155, v155 row_shr:4 row_mask:0xf bank_mask:0xf
	v_mul_f32_dpp v156, v156, v156 row_shr:4 row_mask:0xf bank_mask:0xf
	v_mul_f32_dpp v157, v157, v157 row_shr:4 row_mask:0xf bank_mask:0xf
	v_mul_f32_dpp v158, v158, v158 row_shr:4 row_mask:0xf bank_mask:0xf
	v_mul_f32_dpp v159, v159, v159 row_shr:4 row_mask:0xf bank_mask:0xf
	v_mul_f32_dpp v128, v128, v128 row_shr:8 row_mask:0xf bank_mask:0xf
	v_mul_f32_dpp v129, v129, v129 row_shr:8 row_mask:0xf bank_mask:0xf
	v_mul_f32_dpp v130, v130, v130 row_shr:8 row_mask:0xf bank_mask:0xf
	v_mul_f32_dpp v131, v131, v131 row_shr:8 row_mask:0xf bank_mask:0xf
	v_mul_f32_dpp v132, v132, v132 row_shr:8 row_mask:0xf bank_mask:0xf
	v_mul_f32_dpp v133, v133, v133 row_shr:8 row_mask:0xf bank_mask:0xf
	v_mul_f32_dpp v134, v134, v134 row_shr:8 row_mask:0xf bank_mask:0xf
	v_mul_f32_dpp v135, v135, v135 row_shr:8 row_mask:0xf bank_mask:0xf
	v_mul_f32_dpp v136, v136, v136 row_shr:8 row_mask:0xf bank_mask:0xf
	v_mul_f32_dpp v137, v137, v137 row_shr:8 row_mask:0xf bank_mask:0xf
	v_mul_f32_dpp v138, v138, v138 row_shr:8 row_mask:0xf bank_mask:0xf
	v_mul_f32_dpp v139, v139, v139 row_shr:8 row_mask:0xf bank_mask:0xf
	v_mul_f32_dpp v140, v140, v140 row_shr:8 row_mask:0xf bank_mask:0xf
	v_mul_f32_dpp v141, v141, v141 row_shr:8 row_mask:0xf bank_mask:0xf
	v_mul_f32_dpp v142, v142, v142 row_shr:8 row_mask:0xf bank_mask:0xf
	v_mul_f32_dpp v143, v143, v143 row_shr:8 row_mask:0xf bank_mask:0xf
	v_mul_f32_dpp v144, v144, v144 row_shr:8 row_mask:0xf bank_mask:0xf
	v_mul_f32_dpp v145, v145, v145 row_shr:8 row_mask:0xf bank_mask:0xf
	v_mul_f32_dpp v146, v146, v146 row_shr:8 row_mask:0xf bank_mask:0xf
	v_mul_f32_dpp v147, v147, v147 row_shr:8 row_mask:0xf bank_mask:0xf
	v_mul_f32_dpp v148, v148, v148 row_shr:8 row_mask:0xf bank_mask:0xf
	v_mul_f32_dpp v149, v149, v149 row_shr:8 row_mask:0xf bank_mask:0xf
	v_mul_f32_dpp v150, v150, v150 row_shr:8 row_mask:0xf bank_mask:0xf
	v_mul_f32_dpp v151, v151, v151 row_shr:8 row_mask:0xf bank_mask:0xf
	v_mul_f32_dpp v152, v152, v152 row_shr:8 row_mask:0xf bank_mask:0xf
	v_mul_f32_dpp v153, v153, v153 row_shr:8 row_mask:0xf bank_mask:0xf
	v_mul_f32_dpp v154, v154, v154 row_shr:8 row_mask:0xf bank_mask:0xf
	v_mul_f32_dpp v155, v155, v155 row_shr:8 row_mask:0xf bank_mask:0xf
	v_mul_f32_dpp v156, v156, v156 row_shr:8 row_mask:0xf bank_mask:0xf
	v_mul_f32_dpp v157, v157, v157 row_shr:8 row_mask:0xf bank_mask:0xf
	v_mul_f32_dpp v158, v158, v158 row_shr:8 row_mask:0xf bank_mask:0xf
	v_mul_f32_dpp v159, v159, v159 row_shr:8 row_mask:0xf bank_mask:0xf
	v_mul_f32_dpp v128, v128, v128 row_bcast:15 row_mask:0xa bank_mask:0xf
	v_mul_f32_dpp v129, v129, v129 row_bcast:15 row_mask:0xa bank_mask:0xf
	v_mul_f32_dpp v130, v130, v130 row_bcast:15 row_mask:0xa bank_mask:0xf
	v_mul_f32_dpp v131, v131, v131 row_bcast:15 row_mask:0xa bank_mask:0xf
	v_mul_f32_dpp v132, v132, v132 row_bcast:15 row_mask:0xa bank_mask:0xf
	v_mul_f32_dpp v133, v133, v133 row_bcast:15 row_mask:0xa bank_mask:0xf
	v_mul_f32_dpp v134, v134, v134 row_bcast:15 row_mask:0xa bank_mask:0xf
	v_mul_f32_dpp v135, v135, v135 row_bcast:15 row_mask:0xa bank_mask:0xf
	v_mul_f32_dpp v136, v136, v136 row_bcast:15 row_mask:0xa bank_mask:0xf
	v_mul_f32_dpp v137, v137, v137 row_bcast:15 row_mask:0xa bank_mask:0xf
	v_mul_f32_dpp v138, v138, v138 row_bcast:15 row_mask:0xa bank_mask:0xf
	v_mul_f32_dpp v139, v139, v139 row_bcast:15 row_mask:0xa bank_mask:0xf
	v_mul_f32_dpp v140, v140, v140 row_bcast:15 row_mask:0xa bank_mask:0xf
	v_mul_f32_dpp v141, v141, v141 row_bcast:15 row_mask:0xa bank_mask:0xf
	v_mul_f32_dpp v142, v142, v142 row_bcast:15 row_mask:0xa bank_mask:0xf
	v_mul_f32_dpp v143, v143, v143 row_bcast:15 row_mask:0xa bank_mask:0xf
	v_mul_f32_dpp v144, v144, v144 row_bcast:15 row_mask:0xa bank_mask:0xf
	v_mul_f32_dpp v145, v145, v145 row_bcast:15 row_mask:0xa bank_mask:0xf
	v_mul_f32_dpp v146, v146, v146 row_bcast:15 row_mask:0xa bank_mask:0xf
	v_mul_f32_dpp v147, v147, v147 row_bcast:15 row_mask:0xa bank_mask:0xf
	v_mul_f32_dpp v148, v148, v148 row_bcast:15 row_mask:0xa bank_mask:0xf
	v_mul_f32_dpp v149, v149, v149 row_bcast:15 row_mask:0xa bank_mask:0xf
	v_mul_f32_dpp v150, v150, v150 row_bcast:15 row_mask:0xa bank_mask:0xf
	v_mul_f32_dpp v151, v151, v151 row_bcast:15 row_mask:0xa bank_mask:0xf
	v_mul_f32_dpp v152, v152, v152 row_bcast:15 row_mask:0xa bank_mask:0xf
	v_mul_f32_dpp v153, v153, v153 row_bcast:15 row_mask:0xa bank_mask:0xf
	v_mul_f32_dpp v154, v154, v154 row_bcast:15 row_mask:0xa bank_mask:0xf
	v_mul_f32_dpp v155, v155, v155 row_bcast:15 row_mask:0xa bank_mask:0xf
	v_mul_f32_dpp v156, v156, v156 row_bcast:15 row_mask:0xa bank_mask:0xf
	v_mul_f32_dpp v157, v157, v157 row_bcast:15 row_mask:0xa bank_mask:0xf
	v_mul_f32_dpp v158, v158, v158 row_bcast:15 row_mask:0xa bank_mask:0xf
	v_mul_f32_dpp v159, v159, v159 row_bcast:15 row_mask:0xa bank_mask:0xf
	v_mul_f32_dpp v128, v128, v128 row_bcast:31 row_mask:0xc bank_mask:0xf
	v_mul_f32_dpp v129, v129, v129 row_bcast:31 row_mask:0xc bank_mask:0xf
	v_mul_f32_dpp v130, v130, v130 row_bcast:31 row_mask:0xc bank_mask:0xf
	v_mul_f32_dpp v131, v131, v131 row_bcast:31 row_mask:0xc bank_mask:0xf
	v_mul_f32_dpp v132, v132, v132 row_bcast:31 row_mask:0xc bank_mask:0xf
	v_mul_f32_dpp v133, v133, v133 row_bcast:31 row_mask:0xc bank_mask:0xf
	v_mul_f32_dpp v134, v134, v134 row_bcast:31 row_mask:0xc bank_mask:0xf
	v_mul_f32_dpp v135, v135, v135 row_bcast:31 row_mask:0xc bank_mask:0xf
	v_mul_f32_dpp v136, v136, v136 row_bcast:31 row_mask:0xc bank_mask:0xf
	v_mul_f32_dpp v137, v137, v137 row_bcast:31 row_mask:0xc bank_mask:0xf
	v_mul_f32_dpp v138, v138, v138 row_bcast:31 row_mask:0xc bank_mask:0xf
	v_mul_f32_dpp v139, v139, v139 row_bcast:31 row_mask:0xc bank_mask:0xf
	v_mul_f32_dpp v140, v140, v140 row_bcast:31 row_mask:0xc bank_mask:0xf
	v_mul_f32_dpp v141, v141, v141 row_bcast:31 row_mask:0xc bank_mask:0xf
	v_mul_f32_dpp v142, v142, v142 row_bcast:31 row_mask:0xc bank_mask:0xf
	v_mul_f32_dpp v143, v143, v143 row_bcast:31 row_mask:0xc bank_mask:0xf
	v_mul_f32_dpp v144, v144, v144 row_bcast:31 row_mask:0xc bank_mask:0xf
	v_mul_f32_dpp v145, v145, v145 row_bcast:31 row_mask:0xc bank_mask:0xf
	v_mul_f32_dpp v146, v146, v146 row_bcast:31 row_mask:0xc bank_mask:0xf
	v_mul_f32_dpp v147, v147, v147 row_bcast:31 row_mask:0xc bank_mask:0xf
	v_mul_f32_dpp v148, v148, v148 row_bcast:31 row_mask:0xc bank_mask:0xf
	v_mul_f32_dpp v149, v149, v149 row_bcast:31 row_mask:0xc bank_mask:0xf
	v_mul_f32_dpp v150, v150, v150 row_bcast:31 row_mask:0xc bank_mask:0xf
	v_mul_f32_dpp v151, v151, v151 row_bcast:31 row_mask:0xc bank_mask:0xf
	v_mul_f32_dpp v152, v152, v152 row_bcast:31 row_mask:0xc bank_mask:0xf
	v_mul_f32_dpp v153, v153, v153 row_bcast:31 row_mask:0xc bank_mask:0xf
	v_mul_f32_dpp v154, v154, v154 row_bcast:31 row_mask:0xc bank_mask:0xf
	v_mul_f32_dpp v155, v155, v155 row_bcast:31 row_mask:0xc bank_mask:0xf
	v_mul_f32_dpp v156, v156, v156 row_bcast:31 row_mask:0xc bank_mask:0xf
	v_mul_f32_dpp v157, v157, v157 row_bcast:31 row_mask:0xc bank_mask:0xf
	v_mul_f32_dpp v158, v158, v158 row_bcast:31 row_mask:0xc bank_mask:0xf
	v_mul_f32_dpp v159, v159, v159 row_bcast:31 row_mask:0xc bank_mask:0xf
	s_waitcnt lgkmcnt(0)
	s_cmp_eq_u32 s70, 31
	s_cbranch_scc1 .Lh2_prep_last
	v_add_u32_e32 v228, s33, v228
	v_add_u32_e32 v230, s33, v230
	v_add_u32_e32 v231, s33, v231
	v_add_u32_e32 v232, s33, v232
	s_add_u32 m0, s71, 0
	s_nop 0
	global_load_lds_dwordx4 v228, s[14:15]
	s_add_u32 m0, s71, 4096
	s_nop 0
	global_load_lds_dwordx4 v228, s[30:31]
	s_add_u32 m0, s71, 1024
	s_nop 0
	global_load_lds_dwordx4 v230, s[14:15]
	s_add_u32 m0, s71, 5120
	s_nop 0
	global_load_lds_dwordx4 v230, s[30:31]
	s_add_u32 m0, s71, 2048
	s_nop 0
	global_load_lds_dwordx4 v231, s[14:15]
	s_add_u32 m0, s71, 6144
	s_nop 0
	global_load_lds_dwordx4 v231, s[30:31]
	s_add_u32 m0, s71, 3072
	s_nop 0
	global_load_lds_dwordx4 v232, s[14:15]
	s_add_u32 m0, s71, 7168
	s_nop 0
	global_load_lds_dwordx4 v232, s[30:31]
.Lh2_prep_last:
	s_mov_b32 exec_lo, 0
	s_brev_b32 exec_hi, 1
	ds_write_b128 v247, v[128:131] offset:512
	ds_write_b128 v247, v[132:135] offset:528
	ds_write_b128 v247, v[136:139] offset:544
	ds_write_b128 v247, v[140:143] offset:560
	ds_write_b128 v247, v[144:147] offset:576
	ds_write_b128 v247, v[148:151] offset:592
	ds_write_b128 v247, v[152:155] offset:608
	ds_write_b128 v247, v[156:159] offset:624
	s_mov_b64 exec, -1
	v_rcp_f32_e32 v220, v128
	v_rcp_f32_e32 v221, v129
	v_lshlrev_b32_e32 v218, 16, v234
	v_and_b32_e32 v219, 0xffff0000, v234
	v_pk_mul_f32 v[218:219], v[128:129], v[218:219]
	v_pk_mul_f32 v[220:221], v[220:221], v[96:97]
	v_cvt_pk_bf16_f32 v202, v218, v219
	v_cvt_pk_bf16_f32 v184, v220, v221
	v_rcp_f32_e32 v220, v130
	v_rcp_f32_e32 v221, v131
	v_lshlrev_b32_e32 v218, 16, v235
	v_and_b32_e32 v219, 0xffff0000, v235
	v_pk_mul_f32 v[218:219], v[130:131], v[218:219]
	v_pk_mul_f32 v[220:221], v[220:221], v[98:99]
	v_cvt_pk_bf16_f32 v203, v218, v219
	v_cvt_pk_bf16_f32 v185, v220, v221
	v_rcp_f32_e32 v220, v132
	v_rcp_f32_e32 v221, v133
	v_lshlrev_b32_e32 v218, 16, v236
	v_and_b32_e32 v219, 0xffff0000, v236
	v_pk_mul_f32 v[218:219], v[132:133], v[218:219]
	v_pk_mul_f32 v[220:221], v[220:221], v[100:101]
	v_cvt_pk_bf16_f32 v204, v218, v219
	v_cvt_pk_bf16_f32 v186, v220, v221
	v_rcp_f32_e32 v220, v134
	v_rcp_f32_e32 v221, v135
	v_lshlrev_b32_e32 v218, 16, v237
	v_and_b32_e32 v219, 0xffff0000, v237
	v_pk_mul_f32 v[218:219], v[134:135], v[218:219]
	v_pk_mul_f32 v[220:221], v[220:221], v[102:103]
	v_cvt_pk_bf16_f32 v205, v218, v219
	v_cvt_pk_bf16_f32 v187, v220, v221
	v_rcp_f32_e32 v220, v136
	v_rcp_f32_e32 v221, v137
	v_lshlrev_b32_e32 v218, 16, v238
	v_and_b32_e32 v219, 0xffff0000, v238
	v_pk_mul_f32 v[218:219], v[136:137], v[218:219]
	v_pk_mul_f32 v[220:221], v[220:221], v[104:105]
	v_cvt_pk_bf16_f32 v206, v218, v219
	v_cvt_pk_bf16_f32 v188, v220, v221
	v_rcp_f32_e32 v220, v138
	v_rcp_f32_e32 v221, v139
	v_lshlrev_b32_e32 v218, 16, v239
	v_and_b32_e32 v219, 0xffff0000, v239
	v_pk_mul_f32 v[218:219], v[138:139], v[218:219]
	v_pk_mul_f32 v[220:221], v[220:221], v[106:107]
	v_cvt_pk_bf16_f32 v207, v218, v219
	v_cvt_pk_bf16_f32 v189, v220, v221
	v_rcp_f32_e32 v220, v140
	v_rcp_f32_e32 v221, v141
	v_lshlrev_b32_e32 v218, 16, v240
	v_and_b32_e32 v219, 0xffff0000, v240
	v_pk_mul_f32 v[218:219], v[140:141], v[218:219]
	v_pk_mul_f32 v[220:221], v[220:221], v[108:109]
	v_cvt_pk_bf16_f32 v208, v218, v219
	v_cvt_pk_bf16_f32 v190, v220, v221
	v_rcp_f32_e32 v220, v142
	v_rcp_f32_e32 v221, v143
	v_lshlrev_b32_e32 v218, 16, v241
	v_and_b32_e32 v219, 0xffff0000, v241
	v_pk_mul_f32 v[218:219], v[142:143], v[218:219]
	v_pk_mul_f32 v[220:221], v[220:221], v[110:111]
	v_cvt_pk_bf16_f32 v209, v218, v219
	v_cvt_pk_bf16_f32 v191, v220, v221
	v_rcp_f32_e32 v220, v144
	v_rcp_f32_e32 v221, v145
	v_lshlrev_b32_e32 v218, 16, v242
	v_and_b32_e32 v219, 0xffff0000, v242
	v_pk_mul_f32 v[218:219], v[144:145], v[218:219]
	v_pk_mul_f32 v[220:221], v[220:221], v[112:113]
	v_cvt_pk_bf16_f32 v210, v218, v219
	v_cvt_pk_bf16_f32 v192, v220, v221
	v_rcp_f32_e32 v220, v146
	v_rcp_f32_e32 v221, v147
	v_lshlrev_b32_e32 v218, 16, v243
	v_and_b32_e32 v219, 0xffff0000, v243
	v_pk_mul_f32 v[218:219], v[146:147], v[218:219]
	v_pk_mul_f32 v[220:221], v[220:221], v[114:115]
	v_cvt_pk_bf16_f32 v211, v218, v219
	v_cvt_pk_bf16_f32 v193, v220, v221
	v_rcp_f32_e32 v220, v148
	v_rcp_f32_e32 v221, v149
	v_lshlrev_b32_e32 v218, 16, v244
	v_and_b32_e32 v219, 0xffff0000, v244
	v_pk_mul_f32 v[218:219], v[148:149], v[218:219]
	v_pk_mul_f32 v[220:221], v[220:221], v[116:117]
	v_cvt_pk_bf16_f32 v212, v218, v219
	v_cvt_pk_bf16_f32 v194, v220, v221
	v_rcp_f32_e32 v220, v150
	v_rcp_f32_e32 v221, v151
	v_lshlrev_b32_e32 v218, 16, v245
	v_and_b32_e32 v219, 0xffff0000, v245
	v_pk_mul_f32 v[218:219], v[150:151], v[218:219]
	v_pk_mul_f32 v[220:221], v[220:221], v[118:119]
	v_cvt_pk_bf16_f32 v213, v218, v219
	v_cvt_pk_bf16_f32 v195, v220, v221
	v_rcp_f32_e32 v220, v152
	v_rcp_f32_e32 v221, v153
	v_lshlrev_b32_e32 v218, 16, v168
	v_and_b32_e32 v219, 0xffff0000, v168
	v_pk_mul_f32 v[218:219], v[152:153], v[218:219]
	v_pk_mul_f32 v[220:221], v[220:221], v[120:121]
	v_cvt_pk_bf16_f32 v214, v218, v219
	v_cvt_pk_bf16_f32 v196, v220, v221
	v_rcp_f32_e32 v220, v154
	v_rcp_f32_e32 v221, v155
	v_lshlrev_b32_e32 v218, 16, v169
	v_and_b32_e32 v219, 0xffff0000, v169
	v_pk_mul_f32 v[218:219], v[154:155], v[218:219]
	v_pk_mul_f32 v[220:221], v[220:221], v[122:123]
	v_cvt_pk_bf16_f32 v215, v218, v219
	v_cvt_pk_bf16_f32 v197, v220, v221
	v_rcp_f32_e32 v220, v156
	v_rcp_f32_e32 v221, v157
	v_lshlrev_b32_e32 v218, 16, v170
	v_and_b32_e32 v219, 0xffff0000, v170
	v_pk_mul_f32 v[218:219], v[156:157], v[218:219]
	v_pk_mul_f32 v[220:221], v[220:221], v[124:125]
	v_cvt_pk_bf16_f32 v216, v218, v219
	v_cvt_pk_bf16_f32 v198, v220, v221
	v_rcp_f32_e32 v220, v158
	v_rcp_f32_e32 v221, v159
	v_lshlrev_b32_e32 v218, 16, v171
	v_and_b32_e32 v219, 0xffff0000, v171
	v_pk_mul_f32 v[218:219], v[158:159], v[218:219]
	v_pk_mul_f32 v[220:221], v[220:221], v[126:127]
	v_cvt_pk_bf16_f32 v217, v218, v219
	v_cvt_pk_bf16_f32 v199, v220, v221
	ds_write_b128 v222, v[184:187] offset:17408
	ds_write_b128 v223, v[188:191] offset:17408
	ds_write_b128 v224, v[192:195] offset:17408
	ds_write_b128 v225, v[196:199] offset:17408
	ds_write_b128 v227, v[202:205]
	ds_write_b128 v227, v[206:209] offset:16
	ds_write_b128 v227, v[210:213] offset:32
	ds_write_b128 v227, v[214:217] offset:48
	s_cmp_eq_u32 s70, 31
	s_cbranch_scc1 .Lh2_prep_last_w0
	s_waitcnt vmcnt(8)
	s_branch .Lh2_prep_last_w1

.Lh2_prep_last_w1:
	s_waitcnt lgkmcnt(0)
	s_barrier
	s_add_u32 s70, s70, 1
	s_cmp_lt_u32 s70, 32
	s_cbranch_scc1 .Lh2_prep_loop
	s_barrier
	s_branch .Lh2_done
.Lh2_mfma:
	s_sub_u32 s1, s0, 4
	v_and_b32_e32 v144, 63, v200
	v_and_b32_e32 v145, 31, v144
	v_lshrrev_b32_e32 v146, 5, v144
	v_bfe_u32 v147, v144, 4, 1
	v_bfe_u32 v148, v144, 2, 2
	v_and_b32_e32 v149, 3, v144
	v_and_b32_e32 v150, 3, v145
	v_bfe_u32 v151, v145, 2, 2
	v_xor_b32_e32 v152, 0, v150
	v_lshlrev_b32_e32 v152, 6, v152
	v_or_b32_e32 v153, 0, v146
	v_xor_b32_e32 v153, v153, v151
	v_lshl_add_u32 v152, v153, 4, v152
	v_lshl_add_u32 v226, v145, 8, v152
	v_xor_b32_e32 v152, 0, v150
	v_lshlrev_b32_e32 v152, 6, v152
	v_or_b32_e32 v153, 2, v146
	v_xor_b32_e32 v153, v153, v151
	v_lshl_add_u32 v152, v153, 4, v152
	v_lshl_add_u32 v227, v145, 8, v152
	v_xor_b32_e32 v152, 1, v150
	v_lshlrev_b32_e32 v152, 6, v152
	v_or_b32_e32 v153, 0, v146
	v_xor_b32_e32 v153, v153, v151
	v_lshl_add_u32 v152, v153, 4, v152
	v_lshl_add_u32 v228, v145, 8, v152
	v_xor_b32_e32 v152, 1, v150
	v_lshlrev_b32_e32 v152, 6, v152
	v_or_b32_e32 v153, 2, v146
	v_xor_b32_e32 v153, v153, v151
	v_lshl_add_u32 v152, v153, 4, v152
	v_lshl_add_u32 v229, v145, 8, v152
	v_xor_b32_e32 v152, 2, v150
	v_lshlrev_b32_e32 v152, 6, v152
	v_or_b32_e32 v153, 0, v146
	v_xor_b32_e32 v153, v153, v151
	v_lshl_add_u32 v152, v153, 4, v152
	v_lshl_add_u32 v230, v145, 8, v152
	v_xor_b32_e32 v152, 2, v150
	v_lshlrev_b32_e32 v152, 6, v152
	v_or_b32_e32 v153, 2, v146
	v_xor_b32_e32 v153, v153, v151
	v_lshl_add_u32 v152, v153, 4, v152
	v_lshl_add_u32 v231, v145, 8, v152
	v_xor_b32_e32 v152, 3, v150
	v_lshlrev_b32_e32 v152, 6, v152
	v_or_b32_e32 v153, 0, v146
	v_xor_b32_e32 v153, v153, v151
	v_lshl_add_u32 v152, v153, 4, v152
	v_lshl_add_u32 v232, v145, 8, v152
	v_xor_b32_e32 v152, 3, v150
	v_lshlrev_b32_e32 v152, 6, v152
	v_or_b32_e32 v153, 2, v146
	v_xor_b32_e32 v153, v153, v151
	v_lshl_add_u32 v152, v153, 4, v152
	v_lshl_add_u32 v233, v145, 8, v152
	v_lshrrev_b32_e32 v154, 1, v149
	v_lshl_or_b32 v154, v147, 1, v154
	v_and_b32_e32 v155, 1, v149
	v_lshlrev_b32_e32 v155, 3, v155
	v_lshlrev_b32_e32 v156, 3, v146
	v_add_u32_e32 v156, 0, v156
	v_add_u32_e32 v156, v156, v148
	v_xor_b32_e32 v157, 0, v148
	v_lshlrev_b32_e32 v157, 6, v157
	v_lshlrev_b32_e32 v158, 1, v146
	v_add_u32_e32 v158, 0, v158
	v_and_b32_e32 v158, 3, v158
	v_xor_b32_e32 v158, v158, v154
	v_lshl_add_u32 v157, v158, 4, v157
	v_add_u32_e32 v157, v157, v155
	v_lshl_add_u32 v234, v156, 8, v157
	v_lshlrev_b32_e32 v156, 3, v146
	v_add_u32_e32 v156, 4, v156
	v_add_u32_e32 v156, v156, v148
	v_xor_b32_e32 v157, 0, v148
	v_lshlrev_b32_e32 v157, 6, v157
	v_lshlrev_b32_e32 v158, 1, v146
	v_add_u32_e32 v158, 1, v158
	v_and_b32_e32 v158, 3, v158
	v_xor_b32_e32 v158, v158, v154
	v_lshl_add_u32 v157, v158, 4, v157
	v_add_u32_e32 v157, v157, v155
	v_lshl_add_u32 v235, v156, 8, v157
	v_lshlrev_b32_e32 v156, 3, v146
	v_add_u32_e32 v156, 0, v156
	v_add_u32_e32 v156, v156, v148
	v_xor_b32_e32 v157, 1, v148
	v_lshlrev_b32_e32 v157, 6, v157
	v_lshlrev_b32_e32 v158, 1, v146
	v_add_u32_e32 v158, 0, v158
	v_and_b32_e32 v158, 3, v158
	v_xor_b32_e32 v158, v158, v154
	v_lshl_add_u32 v157, v158, 4, v157
	v_add_u32_e32 v157, v157, v155
	v_lshl_add_u32 v236, v156, 8, v157
	v_lshlrev_b32_e32 v156, 3, v146
	v_add_u32_e32 v156, 4, v156
	v_add_u32_e32 v156, v156, v148
	v_xor_b32_e32 v157, 1, v148
	v_lshlrev_b32_e32 v157, 6, v157
	v_lshlrev_b32_e32 v158, 1, v146
	v_add_u32_e32 v158, 1, v158
	v_and_b32_e32 v158, 3, v158
	v_xor_b32_e32 v158, v158, v154
	v_lshl_add_u32 v157, v158, 4, v157
	v_add_u32_e32 v157, v157, v155
	v_lshl_add_u32 v237, v156, 8, v157
	v_lshlrev_b32_e32 v156, 3, v146
	v_add_u32_e32 v156, 0, v156
	v_add_u32_e32 v156, v156, v148
	v_xor_b32_e32 v157, 2, v148
	v_lshlrev_b32_e32 v157, 6, v157
	v_lshlrev_b32_e32 v158, 1, v146
	v_add_u32_e32 v158, 0, v158
	v_and_b32_e32 v158, 3, v158
	v_xor_b32_e32 v158, v158, v154
	v_lshl_add_u32 v157, v158, 4, v157
	v_add_u32_e32 v157, v157, v155
	v_lshl_add_u32 v238, v156, 8, v157
	v_lshlrev_b32_e32 v156, 3, v146
	v_add_u32_e32 v156, 4, v156
	v_add_u32_e32 v156, v156, v148
	v_xor_b32_e32 v157, 2, v148
	v_lshlrev_b32_e32 v157, 6, v157
	v_lshlrev_b32_e32 v158, 1, v146
	v_add_u32_e32 v158, 1, v158
	v_and_b32_e32 v158, 3, v158
	v_xor_b32_e32 v158, v158, v154
	v_lshl_add_u32 v157, v158, 4, v157
	v_add_u32_e32 v157, v157, v155
	v_lshl_add_u32 v239, v156, 8, v157
	v_lshlrev_b32_e32 v156, 3, v146
	v_add_u32_e32 v156, 0, v156
	v_add_u32_e32 v156, v156, v148
	v_xor_b32_e32 v157, 3, v148
	v_lshlrev_b32_e32 v157, 6, v157
	v_lshlrev_b32_e32 v158, 1, v146
	v_add_u32_e32 v158, 0, v158
	v_and_b32_e32 v158, 3, v158
	v_xor_b32_e32 v158, v158, v154
	v_lshl_add_u32 v157, v158, 4, v157
	v_add_u32_e32 v157, v157, v155
	v_lshl_add_u32 v240, v156, 8, v157
	v_lshlrev_b32_e32 v156, 3, v146
	v_add_u32_e32 v156, 4, v156
	v_add_u32_e32 v156, v156, v148
	v_xor_b32_e32 v157, 3, v148
	v_lshlrev_b32_e32 v157, 6, v157
	v_lshlrev_b32_e32 v158, 1, v146
	v_add_u32_e32 v158, 1, v158
	v_and_b32_e32 v158, 3, v158
	v_xor_b32_e32 v158, v158, v154
	v_lshl_add_u32 v157, v158, 4, v157
	v_add_u32_e32 v157, v157, v155
	v_lshl_add_u32 v241, v156, 8, v157
	v_lshlrev_b32_e32 v156, 3, v146
	v_add_u32_e32 v156, 0, v156
	v_add_u32_e32 v156, v156, v148
	v_xor_b32_e32 v157, s1, v148
	v_lshlrev_b32_e32 v157, 6, v157
	v_lshlrev_b32_e32 v158, 1, v146
	v_add_u32_e32 v158, 0, v158
	v_and_b32_e32 v158, 3, v158
	v_xor_b32_e32 v158, v158, v154
	v_lshl_add_u32 v157, v158, 4, v157
	v_add_u32_e32 v157, v157, v155
	v_lshl_add_u32 v242, v156, 8, v157
	v_lshlrev_b32_e32 v156, 3, v146
	v_add_u32_e32 v156, 4, v156
	v_add_u32_e32 v156, v156, v148
	v_xor_b32_e32 v157, s1, v148
	v_lshlrev_b32_e32 v157, 6, v157
	v_lshlrev_b32_e32 v158, 1, v146
	v_add_u32_e32 v158, 1, v158
	v_and_b32_e32 v158, 3, v158
	v_xor_b32_e32 v158, v158, v154
	v_lshl_add_u32 v157, v158, 4, v157
	v_add_u32_e32 v157, v157, v155
	v_lshl_add_u32 v243, v156, 8, v157
	v_lshlrev_b32_e32 v156, 2, v146
	v_add_u32_e32 v156, 0, v156
	v_add_u32_e32 v156, v156, v148
	v_xor_b32_e32 v157, s1, v148
	v_lshlrev_b32_e32 v157, 6, v157
	v_add_u32_e32 v158, 0, v146
	v_and_b32_e32 v158, 3, v158
	v_xor_b32_e32 v158, v158, v154
	v_lshl_add_u32 v157, v158, 4, v157
	v_add_u32_e32 v157, v157, v155
	v_lshl_add_u32 v244, v156, 8, v157
	v_lshlrev_b32_e32 v156, 2, v146
	v_add_u32_e32 v156, 8, v156
	v_add_u32_e32 v156, v156, v148
	v_xor_b32_e32 v157, s1, v148
	v_lshlrev_b32_e32 v157, 6, v157
	v_add_u32_e32 v158, 2, v146
	v_and_b32_e32 v158, 3, v158
	v_xor_b32_e32 v158, v158, v154
	v_lshl_add_u32 v157, v158, 4, v157
	v_add_u32_e32 v157, v157, v155
	v_lshl_add_u32 v245, v156, 8, v157
	v_mov_b32_e32 v156, 0x110
	v_add_u32_e32 v157, 0, v145
	v_mul_lo_u32 v157, v157, v156
	v_add_u32_e32 v158, 0x10400, v157
	v_lshl_add_u32 v247, v146, 4, v158
	v_lshl_add_u32 v251, v146, 3, v158
	v_add_u32_e32 v158, 0x14800, v157
	v_lshl_add_u32 v248, v146, 4, v158
	v_lshl_add_u32 v252, v146, 3, v158
	v_add_u32_e32 v157, 32, v145
	v_mul_lo_u32 v157, v157, v156
	v_add_u32_e32 v158, 0x10400, v157
	v_lshl_add_u32 v249, v146, 4, v158
	v_lshl_add_u32 v253, v146, 3, v158
	v_add_u32_e32 v158, 0x14800, v157
	v_lshl_add_u32 v250, v146, 4, v158
	v_lshl_add_u32 v254, v146, 3, v158
	v_lshlrev_b32_e32 v255, 4, v146
	v_lshlrev_b32_e32 v156, 2, v146
	v_add_u32_e32 v157, 0, v156
	v_cmp_gt_u32_e64 s[38:39], v157, v145
	v_add_u32_e32 v157, 1, v156
	v_cmp_gt_u32_e64 s[40:41], v157, v145
	v_add_u32_e32 v157, 2, v156
	v_cmp_gt_u32_e64 s[42:43], v157, v145
	v_add_u32_e32 v157, 3, v156
	v_cmp_gt_u32_e64 s[44:45], v157, v145
	v_add_u32_e32 v157, 8, v156
	v_cmp_gt_u32_e64 s[46:47], v157, v145
	v_add_u32_e32 v157, 9, v156
	v_cmp_gt_u32_e64 s[48:49], v157, v145
	v_add_u32_e32 v157, 10, v156
	v_cmp_gt_u32_e64 s[50:51], v157, v145
	v_add_u32_e32 v157, 11, v156
	v_cmp_gt_u32_e64 s[52:53], v157, v145
	v_add_u32_e32 v157, 16, v156
	v_cmp_gt_u32_e64 s[54:55], v157, v145
	v_add_u32_e32 v157, 17, v156
	v_cmp_gt_u32_e64 s[56:57], v157, v145
	v_add_u32_e32 v157, 18, v156
	v_cmp_gt_u32_e64 s[58:59], v157, v145
	v_add_u32_e32 v157, 19, v156
	v_cmp_gt_u32_e64 s[60:61], v157, v145
	v_add_u32_e32 v157, 24, v156
	v_cmp_gt_u32_e64 s[62:63], v157, v145
	v_add_u32_e32 v157, 25, v156
	v_cmp_gt_u32_e64 s[64:65], v157, v145
	v_add_u32_e32 v157, 26, v156
	v_cmp_gt_u32_e64 s[66:67], v157, v145
	v_add_u32_e32 v157, 27, v156
	v_cmp_gt_u32_e64 s[68:69], v157, v145
	s_mul_i32 s13, s1, 0xa00
	s_add_u32 s13, s13, 0x18c00
	v_mov_b32_e32 v156, 0x50
	v_mul_lo_u32 v157, v145, v156
	v_lshl_add_u32 v157, v146, 3, v157
	v_add_u32_e32 v168, s13, v157
	v_lshrrev_b32_e32 v157, 2, v144
	v_mul_lo_u32 v158, v157, v156
	v_lshl_add_u32 v158, v149, 4, v158
	v_add_u32_e32 v169, s13, v158
	v_add_u32_e32 v170, 0x500, v169
	s_lshl_b32 s13, s8, 12
	v_add_u32_e32 v158, s13, v157
	s_add_u32 s17, s13, 0xfff
	v_sub_u32_e32 v159, s17, v157
	s_cmp_eq_u32 s12, 0
	s_cselect_b64 s[18:19], -1, 0
	v_cndmask_b32_e64 v158, v159, v158, s[18:19]
	v_lshlrev_b32_e32 v158, 10, v158
	v_lshl_add_u32 v171, v149, 4, v158
	s_mov_b32 s33, 0x10000
	s_sub_u32 s13, 0, s33
	s_cmp_eq_u32 s12, 0
	s_cselect_b32 s33, s33, s13
	s_mov_b32 s71, 0
	s_ashr_i32 s72, s33, 2
	s_ashr_i32 s73, s33, 1
	s_add_i32 s75, s73, s72
	s_mov_b32 s13, 0x35000000
	s_cmp_eq_u32 s12, 0
	s_cselect_b32 s13, 0x2d000000, s13
	s_lshl_b32 s17, s9, 8
	s_add_u32 s13, s13, s17
	s_lshl_b32 s17, s1, 6
	s_add_u32 s13, s13, s17
	s_add_u32 s14, s26, s13
	s_addc_u32 s15, s27, 0
	v_mov_b64_e32 v[0:1], 0
	v_mov_b64_e32 v[2:3], 0
	v_mov_b64_e32 v[4:5], 0
	v_mov_b64_e32 v[6:7], 0
	v_mov_b64_e32 v[8:9], 0
	v_mov_b64_e32 v[10:11], 0
	v_mov_b64_e32 v[12:13], 0
	v_mov_b64_e32 v[14:15], 0
	v_mov_b64_e32 v[16:17], 0
	v_mov_b64_e32 v[18:19], 0
	v_mov_b64_e32 v[20:21], 0
	v_mov_b64_e32 v[22:23], 0
	v_mov_b64_e32 v[24:25], 0
	v_mov_b64_e32 v[26:27], 0
	v_mov_b64_e32 v[28:29], 0
	v_mov_b64_e32 v[30:31], 0
	v_mov_b64_e32 v[32:33], 0
	v_mov_b64_e32 v[34:35], 0
	v_mov_b64_e32 v[36:37], 0
	v_mov_b64_e32 v[38:39], 0
	v_mov_b64_e32 v[40:41], 0
	v_mov_b64_e32 v[42:43], 0
	v_mov_b64_e32 v[44:45], 0
	v_mov_b64_e32 v[46:47], 0
	v_mov_b64_e32 v[48:49], 0
	v_mov_b64_e32 v[50:51], 0
	v_mov_b64_e32 v[52:53], 0
	v_mov_b64_e32 v[54:55], 0
	v_mov_b64_e32 v[56:57], 0
	v_mov_b64_e32 v[58:59], 0
	v_mov_b64_e32 v[60:61], 0
	v_mov_b64_e32 v[62:63], 0
	s_mov_b32 s70, 0
	s_barrier
.Lh2_mfma_loop:
	ds_read_b128 v[64:67], v247
	ds_read_b128 v[144:147], v226 offset:1024
	ds_read_b128 v[68:71], v247 offset:32
	ds_read_b128 v[148:151], v227 offset:1024
	ds_read_b128 v[72:75], v247 offset:64
	ds_read_b128 v[152:155], v228 offset:1024
	ds_read_b128 v[76:79], v247 offset:96
	ds_read_b128 v[156:159], v229 offset:1024
	ds_read_b128 v[80:83], v247 offset:128
	ds_read_b128 v[184:187], v230 offset:1024
	ds_read_b128 v[84:87], v247 offset:160
	ds_read_b128 v[188:191], v231 offset:1024
	s_waitcnt lgkmcnt(10)
	v_mfma_f32_32x32x16_bf16 v[96:111], v[144:147], v[64:67], 0
	ds_read_b128 v[88:91], v247 offset:192
	ds_read_b128 v[192:195], v232 offset:1024
	s_waitcnt lgkmcnt(10)
	v_mfma_f32_32x32x16_bf16 v[96:111], v[148:151], v[68:71], v[96:111]
	ds_read_b128 v[92:95], v247 offset:224
	ds_read_b128 v[196:199], v233 offset:1024
	s_waitcnt lgkmcnt(10)
	v_mfma_f32_32x32x16_bf16 v[96:111], v[152:155], v[72:75], v[96:111]
	ds_read_b64_tr_b16 v[202:203], v244 offset:33792
	ds_read_b64_tr_b16 v[204:205], v245 offset:33792
	s_waitcnt lgkmcnt(10)
	v_mfma_f32_32x32x16_bf16 v[96:111], v[156:159], v[76:79], v[96:111]
	ds_read_b64_tr_b16 v[206:207], v244 offset:37888
	ds_read_b64_tr_b16 v[208:209], v245 offset:37888
	s_waitcnt lgkmcnt(10)
	v_mfma_f32_32x32x16_bf16 v[96:111], v[184:187], v[80:83], v[96:111]
	ds_read2_b64 v[210:213], v251 offset0:0 offset1:2
	ds_read2_b64 v[214:217], v251 offset0:4 offset1:6
	s_waitcnt lgkmcnt(10)
	v_mfma_f32_32x32x16_bf16 v[96:111], v[188:191], v[84:87], v[96:111]
	ds_read2_b64 v[144:147], v251 offset0:8 offset1:10
	ds_read2_b64 v[148:151], v251 offset0:12 offset1:14
	s_waitcnt lgkmcnt(10)
	v_mfma_f32_32x32x16_bf16 v[96:111], v[192:195], v[88:91], v[96:111]
	ds_read2_b64 v[152:155], v251 offset0:16 offset1:18
	ds_read2_b64 v[156:159], v251 offset0:20 offset1:22
	s_waitcnt lgkmcnt(10)
	v_mfma_f32_32x32x16_bf16 v[96:111], v[196:199], v[92:95], v[96:111]
	ds_read2_b64 v[184:187], v251 offset0:24 offset1:26
	ds_read2_b64 v[188:191], v251 offset0:28 offset1:30
	s_waitcnt lgkmcnt(10)
	s_nop 8
	v_cndmask_b32_e64 v96, v96, 0, s[38:39]
	v_cndmask_b32_e64 v97, v97, 0, s[40:41]
	v_cndmask_b32_e64 v98, v98, 0, s[42:43]
	v_cndmask_b32_e64 v99, v99, 0, s[44:45]
	v_cndmask_b32_e64 v100, v100, 0, s[46:47]
	v_cndmask_b32_e64 v101, v101, 0, s[48:49]
	v_cndmask_b32_e64 v102, v102, 0, s[50:51]
	v_cndmask_b32_e64 v103, v103, 0, s[52:53]
	v_cndmask_b32_e64 v104, v104, 0, s[54:55]
	v_cndmask_b32_e64 v105, v105, 0, s[56:57]
	v_cndmask_b32_e64 v106, v106, 0, s[58:59]
	v_cndmask_b32_e64 v107, v107, 0, s[60:61]
	v_cndmask_b32_e64 v108, v108, 0, s[62:63]
	v_cndmask_b32_e64 v109, v109, 0, s[64:65]
	v_cndmask_b32_e64 v110, v110, 0, s[66:67]
	v_cndmask_b32_e64 v111, v111, 0, s[68:69]
	v_cvt_pk_bf16_f32 v96, v96, v97
	v_cvt_pk_bf16_f32 v97, v98, v99
	v_cvt_pk_bf16_f32 v98, v100, v101
	v_cvt_pk_bf16_f32 v99, v102, v103
	v_cvt_pk_bf16_f32 v100, v104, v105
	v_cvt_pk_bf16_f32 v101, v106, v107
	v_cvt_pk_bf16_f32 v102, v108, v109
	v_cvt_pk_bf16_f32 v103, v110, v111
	v_mfma_f32_32x32x16_bf16 v[128:143], v[202:205], v[96:99], 0
	s_waitcnt lgkmcnt(8)
	v_mfma_f32_32x32x16_bf16 v[128:143], v[206:209], v[100:103], v[128:143]
	v_cvt_pk_bf16_f32 v218, v0, v1
	v_cvt_pk_bf16_f32 v219, v2, v3
	v_cvt_pk_bf16_f32 v220, v4, v5
	v_cvt_pk_bf16_f32 v221, v6, v7
	s_waitcnt lgkmcnt(7)
	s_nop 1
	v_mfma_f32_32x32x16_bf16 v[128:143], v[218:221], v[210:213], v[128:143]
	v_cvt_pk_bf16_f32 v222, v8, v9
	v_cvt_pk_bf16_f32 v223, v10, v11
	v_cvt_pk_bf16_f32 v224, v12, v13
	v_cvt_pk_bf16_f32 v225, v14, v15
	s_waitcnt lgkmcnt(6)
	s_nop 1
	v_mfma_f32_32x32x16_bf16 v[128:143], v[222:225], v[214:217], v[128:143]
	v_cvt_pk_bf16_f32 v218, v16, v17
	v_cvt_pk_bf16_f32 v219, v18, v19
	v_cvt_pk_bf16_f32 v220, v20, v21
	v_cvt_pk_bf16_f32 v221, v22, v23
	s_waitcnt lgkmcnt(5)
	s_nop 1
	v_mfma_f32_32x32x16_bf16 v[128:143], v[218:221], v[144:147], v[128:143]
	v_cvt_pk_bf16_f32 v222, v24, v25
	v_cvt_pk_bf16_f32 v223, v26, v27
	v_cvt_pk_bf16_f32 v224, v28, v29
	v_cvt_pk_bf16_f32 v225, v30, v31
	s_waitcnt lgkmcnt(4)
	s_nop 1
	v_mfma_f32_32x32x16_bf16 v[128:143], v[222:225], v[148:151], v[128:143]
	v_cvt_pk_bf16_f32 v218, v32, v33
	v_cvt_pk_bf16_f32 v219, v34, v35
	v_cvt_pk_bf16_f32 v220, v36, v37
	v_cvt_pk_bf16_f32 v221, v38, v39
	s_waitcnt lgkmcnt(3)
	s_nop 1
	v_mfma_f32_32x32x16_bf16 v[128:143], v[218:221], v[152:155], v[128:143]
	v_cvt_pk_bf16_f32 v222, v40, v41
	v_cvt_pk_bf16_f32 v223, v42, v43
	v_cvt_pk_bf16_f32 v224, v44, v45
	v_cvt_pk_bf16_f32 v225, v46, v47
	s_waitcnt lgkmcnt(2)
	s_nop 1
	v_mfma_f32_32x32x16_bf16 v[128:143], v[222:225], v[156:159], v[128:143]
	v_cvt_pk_bf16_f32 v218, v48, v49
	v_cvt_pk_bf16_f32 v219, v50, v51
	v_cvt_pk_bf16_f32 v220, v52, v53
	v_cvt_pk_bf16_f32 v221, v54, v55
	s_waitcnt lgkmcnt(1)
	s_nop 1
	v_mfma_f32_32x32x16_bf16 v[128:143], v[218:221], v[184:187], v[128:143]
	v_cvt_pk_bf16_f32 v222, v56, v57
	v_cvt_pk_bf16_f32 v223, v58, v59
	v_cvt_pk_bf16_f32 v224, v60, v61
	v_cvt_pk_bf16_f32 v225, v62, v63
	s_waitcnt lgkmcnt(0)
	s_nop 1
	v_mfma_f32_32x32x16_bf16 v[128:143], v[222:225], v[188:191], v[128:143]
	ds_read_b128 v[64:67], v249
	ds_read_b128 v[192:195], v226 offset:1024
	ds_read_b128 v[68:71], v249 offset:32
	ds_read_b128 v[196:199], v227 offset:1024
	ds_read_b128 v[72:75], v249 offset:64
	ds_read_b128 v[202:205], v228 offset:1024
	ds_read_b128 v[76:79], v249 offset:96
	ds_read_b128 v[206:209], v229 offset:1024
	ds_read_b128 v[80:83], v249 offset:128
	ds_read_b128 v[210:213], v230 offset:1024
	ds_read_b128 v[84:87], v249 offset:160
	ds_read_b128 v[214:217], v231 offset:1024
	s_waitcnt lgkmcnt(11)
	v_cvt_pk_bf16_f32 v218, v128, v129
	v_cvt_pk_bf16_f32 v219, v130, v131
	v_cvt_pk_bf16_f32 v220, v132, v133
	v_cvt_pk_bf16_f32 v221, v134, v135
	v_cvt_pk_bf16_f32 v222, v136, v137
	v_cvt_pk_bf16_f32 v223, v138, v139
	v_cvt_pk_bf16_f32 v224, v140, v141
	v_cvt_pk_bf16_f32 v225, v142, v143
	ds_write2_b64 v168, v[218:219], v[220:221] offset1:2
	ds_write2_b64 v168, v[222:223], v[224:225] offset0:4 offset1:6
	ds_read_b128 v[218:221], v169
	ds_read_b128 v[222:225], v170
	v_add_u32_e32 v183, s71, v171
	v_add_u32_e32 v201, s72, v171
	s_waitcnt lgkmcnt(0)
	global_store_dwordx4 v183, v[218:221], s[14:15]
	global_store_dwordx4 v201, v[222:225], s[14:15]
	ds_read_b128 v[88:91], v249 offset:192
	ds_read_b128 v[144:147], v232 offset:1024
	ds_read_b128 v[92:95], v249 offset:224
	ds_read_b128 v[148:151], v233 offset:1024
	ds_read_b128 v[152:155], v226 offset:9216
	ds_read_b128 v[156:159], v227 offset:9216
	ds_read_b128 v[184:187], v228 offset:9216
	ds_read_b128 v[188:191], v229 offset:9216
	v_mfma_f32_32x32x16_bf16 v[96:111], v[192:195], v[64:67], 0
	ds_read_b128 v[192:195], v230 offset:9216
	v_mfma_f32_32x32x16_bf16 v[96:111], v[196:199], v[68:71], v[96:111]
	ds_read_b128 v[196:199], v231 offset:9216
	v_mfma_f32_32x32x16_bf16 v[96:111], v[202:205], v[72:75], v[96:111]
	ds_read_b128 v[202:205], v232 offset:9216
	v_mfma_f32_32x32x16_bf16 v[96:111], v[206:209], v[76:79], v[96:111]
	ds_read_b128 v[206:209], v233 offset:9216
	v_mfma_f32_32x32x16_bf16 v[96:111], v[210:213], v[80:83], v[96:111]
	v_mfma_f32_32x32x16_bf16 v[96:111], v[214:217], v[84:87], v[96:111]
	s_waitcnt lgkmcnt(10)
	v_mfma_f32_32x32x16_bf16 v[96:111], v[144:147], v[88:91], v[96:111]
	ds_read_b64_tr_b16 v[210:211], v244 offset:33792
	ds_read_b64_tr_b16 v[212:213], v245 offset:33792
	s_waitcnt lgkmcnt(10)
	v_mfma_f32_32x32x16_bf16 v[96:111], v[148:151], v[92:95], v[96:111]
	ds_read_b64_tr_b16 v[214:215], v244 offset:37888
	ds_read_b64_tr_b16 v[216:217], v245 offset:37888
	s_waitcnt lgkmcnt(11)
	v_mfma_f32_32x32x16_bf16 v[112:127], v[152:155], v[64:67], 0
	s_waitcnt lgkmcnt(10)
	v_mfma_f32_32x32x16_bf16 v[112:127], v[156:159], v[68:71], v[112:127]
	ds_read_b64_tr_b16 v[144:145], v244 offset:41984
	ds_read_b64_tr_b16 v[146:147], v245 offset:41984
	s_waitcnt lgkmcnt(11)
	v_mfma_f32_32x32x16_bf16 v[112:127], v[184:187], v[72:75], v[112:127]
	s_waitcnt lgkmcnt(10)
	v_mfma_f32_32x32x16_bf16 v[112:127], v[188:191], v[76:79], v[112:127]
	ds_read_b64_tr_b16 v[148:149], v244 offset:46080
	ds_read_b64_tr_b16 v[150:151], v245 offset:46080
	s_waitcnt lgkmcnt(11)
	v_mfma_f32_32x32x16_bf16 v[112:127], v[192:195], v[80:83], v[112:127]
	ds_read2_b64 v[152:155], v253 offset0:0 offset1:2
	s_waitcnt lgkmcnt(11)
	v_mfma_f32_32x32x16_bf16 v[112:127], v[196:199], v[84:87], v[112:127]
	ds_read2_b64 v[156:159], v253 offset0:4 offset1:6
	s_waitcnt lgkmcnt(11)
	v_mfma_f32_32x32x16_bf16 v[112:127], v[202:205], v[88:91], v[112:127]
	ds_read2_b64 v[184:187], v253 offset0:8 offset1:10
	s_waitcnt lgkmcnt(11)
	v_mfma_f32_32x32x16_bf16 v[112:127], v[206:209], v[92:95], v[112:127]
	ds_read2_b64 v[188:191], v253 offset0:12 offset1:14
	s_waitcnt lgkmcnt(10)
	v_cvt_pk_bf16_f32 v96, v96, v97
	v_cvt_pk_bf16_f32 v97, v98, v99
	v_cvt_pk_bf16_f32 v98, v100, v101
	v_cvt_pk_bf16_f32 v99, v102, v103
	v_cvt_pk_bf16_f32 v100, v104, v105
	v_cvt_pk_bf16_f32 v101, v106, v107
	v_cvt_pk_bf16_f32 v102, v108, v109
	v_cvt_pk_bf16_f32 v103, v110, v111
	s_nop 1
	v_cndmask_b32_e64 v112, v112, 0, s[38:39]
	v_cndmask_b32_e64 v113, v113, 0, s[40:41]
	v_cndmask_b32_e64 v114, v114, 0, s[42:43]
	v_cndmask_b32_e64 v115, v115, 0, s[44:45]
	v_cndmask_b32_e64 v116, v116, 0, s[46:47]
	v_cndmask_b32_e64 v117, v117, 0, s[48:49]
	v_cndmask_b32_e64 v118, v118, 0, s[50:51]
	v_cndmask_b32_e64 v119, v119, 0, s[52:53]
	v_cndmask_b32_e64 v120, v120, 0, s[54:55]
	v_cndmask_b32_e64 v121, v121, 0, s[56:57]
	v_cndmask_b32_e64 v122, v122, 0, s[58:59]
	v_cndmask_b32_e64 v123, v123, 0, s[60:61]
	v_cndmask_b32_e64 v124, v124, 0, s[62:63]
	v_cndmask_b32_e64 v125, v125, 0, s[64:65]
	v_cndmask_b32_e64 v126, v126, 0, s[66:67]
	v_cndmask_b32_e64 v127, v127, 0, s[68:69]
	v_cvt_pk_bf16_f32 v112, v112, v113
	v_cvt_pk_bf16_f32 v113, v114, v115
	v_cvt_pk_bf16_f32 v114, v116, v117
	v_cvt_pk_bf16_f32 v115, v118, v119
	v_cvt_pk_bf16_f32 v116, v120, v121
	v_cvt_pk_bf16_f32 v117, v122, v123
	v_cvt_pk_bf16_f32 v118, v124, v125
	v_cvt_pk_bf16_f32 v119, v126, v127
	ds_read2_b64 v[192:195], v253 offset0:16 offset1:18
	ds_read2_b64 v[196:199], v253 offset0:20 offset1:22
	v_mfma_f32_32x32x16_bf16 v[128:143], v[210:213], v[96:99], 0
	s_waitcnt lgkmcnt(10)
	v_mfma_f32_32x32x16_bf16 v[128:143], v[214:217], v[100:103], v[128:143]
	ds_read2_b64 v[202:205], v253 offset0:24 offset1:26
	ds_read2_b64 v[206:209], v253 offset0:28 offset1:30
	s_waitcnt lgkmcnt(10)
	v_mfma_f32_32x32x16_bf16 v[128:143], v[144:147], v[112:115], v[128:143]
	ds_read_b64_tr_b16 v[210:211], v242 offset:33792
	ds_read_b64_tr_b16 v[212:213], v243 offset:33792
	s_waitcnt lgkmcnt(10)
	v_mfma_f32_32x32x16_bf16 v[128:143], v[148:151], v[116:119], v[128:143]
	v_cvt_pk_bf16_f32 v218, v0, v1
	v_cvt_pk_bf16_f32 v219, v2, v3
	v_cvt_pk_bf16_f32 v220, v4, v5
	v_cvt_pk_bf16_f32 v221, v6, v7
	ds_read_b64_tr_b16 v[214:215], v234 offset:1024
	ds_read_b64_tr_b16 v[216:217], v235 offset:1024
	s_waitcnt lgkmcnt(11)
	s_nop 1
	v_mfma_f32_32x32x16_bf16 v[128:143], v[218:221], v[152:155], v[128:143]
	v_cvt_pk_bf16_f32 v222, v8, v9
	v_cvt_pk_bf16_f32 v223, v10, v11
	v_cvt_pk_bf16_f32 v224, v12, v13
	v_cvt_pk_bf16_f32 v225, v14, v15
	s_waitcnt lgkmcnt(10)
	s_nop 1
	v_mfma_f32_32x32x16_bf16 v[128:143], v[222:225], v[156:159], v[128:143]
	v_cvt_pk_bf16_f32 v218, v16, v17
	v_cvt_pk_bf16_f32 v219, v18, v19
	v_cvt_pk_bf16_f32 v220, v20, v21
	v_cvt_pk_bf16_f32 v221, v22, v23
	ds_read_b64_tr_b16 v[144:145], v236 offset:1024
	ds_read_b64_tr_b16 v[146:147], v237 offset:1024
	s_waitcnt lgkmcnt(11)
	s_nop 1
	v_mfma_f32_32x32x16_bf16 v[128:143], v[218:221], v[184:187], v[128:143]
	v_cvt_pk_bf16_f32 v222, v24, v25
	v_cvt_pk_bf16_f32 v223, v26, v27
	v_cvt_pk_bf16_f32 v224, v28, v29
	v_cvt_pk_bf16_f32 v225, v30, v31
	s_waitcnt lgkmcnt(10)
	s_nop 1
	v_mfma_f32_32x32x16_bf16 v[128:143], v[222:225], v[188:191], v[128:143]
	v_cvt_pk_bf16_f32 v218, v32, v33
	v_cvt_pk_bf16_f32 v219, v34, v35
	v_cvt_pk_bf16_f32 v220, v36, v37
	v_cvt_pk_bf16_f32 v221, v38, v39
	ds_read_b64_tr_b16 v[148:149], v238 offset:1024
	ds_read_b64_tr_b16 v[150:151], v239 offset:1024
	s_waitcnt lgkmcnt(11)
	s_nop 1
	v_mfma_f32_32x32x16_bf16 v[128:143], v[218:221], v[192:195], v[128:143]
	v_cvt_pk_bf16_f32 v222, v40, v41
	v_cvt_pk_bf16_f32 v223, v42, v43
	v_cvt_pk_bf16_f32 v224, v44, v45
	v_cvt_pk_bf16_f32 v225, v46, v47
	s_waitcnt lgkmcnt(10)
	s_nop 1
	v_mfma_f32_32x32x16_bf16 v[128:143], v[222:225], v[196:199], v[128:143]
	v_cvt_pk_bf16_f32 v218, v48, v49
	v_cvt_pk_bf16_f32 v219, v50, v51
	v_cvt_pk_bf16_f32 v220, v52, v53
	v_cvt_pk_bf16_f32 v221, v54, v55
	ds_read_b64_tr_b16 v[152:153], v240 offset:1024
	ds_read_b64_tr_b16 v[154:155], v241 offset:1024
	s_waitcnt lgkmcnt(11)
	s_nop 1
	v_mfma_f32_32x32x16_bf16 v[128:143], v[218:221], v[202:205], v[128:143]
	v_cvt_pk_bf16_f32 v222, v56, v57
	v_cvt_pk_bf16_f32 v223, v58, v59
	v_cvt_pk_bf16_f32 v224, v60, v61
	v_cvt_pk_bf16_f32 v225, v62, v63
	s_waitcnt lgkmcnt(10)
	s_nop 1
	v_mfma_f32_32x32x16_bf16 v[128:143], v[222:225], v[206:209], v[128:143]
	ds_read_b64_tr_b16 v[156:157], v242 offset:37888
	ds_read_b64_tr_b16 v[158:159], v243 offset:37888
	s_waitcnt lgkmcnt(10)
	s_nop 8
	v_cvt_pk_bf16_f32 v218, v128, v129
	v_cvt_pk_bf16_f32 v219, v130, v131
	v_cvt_pk_bf16_f32 v220, v132, v133
	v_cvt_pk_bf16_f32 v221, v134, v135
	v_cvt_pk_bf16_f32 v222, v136, v137
	v_cvt_pk_bf16_f32 v223, v138, v139
	v_cvt_pk_bf16_f32 v224, v140, v141
	v_cvt_pk_bf16_f32 v225, v142, v143
	ds_write2_b64 v168, v[218:219], v[220:221] offset1:2
	ds_write2_b64 v168, v[222:223], v[224:225] offset0:4 offset1:6
	ds_read_b128 v[218:221], v169
	ds_read_b128 v[222:225], v170
	v_add_u32_e32 v183, s73, v171
	v_add_u32_e32 v201, s75, v171
	s_waitcnt lgkmcnt(0)
	global_store_dwordx4 v183, v[218:221], s[14:15]
	global_store_dwordx4 v201, v[222:225], s[14:15]
	ds_read_b64_tr_b16 v[184:185], v234 offset:5120
	ds_read_b64_tr_b16 v[186:187], v235 offset:5120
	ds_read_b64_tr_b16 v[188:189], v236 offset:5120
	ds_read_b64_tr_b16 v[190:191], v237 offset:5120
	ds_read_b64_tr_b16 v[192:193], v238 offset:5120
	ds_read_b64_tr_b16 v[194:195], v239 offset:5120
	ds_read_b64_tr_b16 v[196:197], v240 offset:5120
	ds_read_b64_tr_b16 v[198:199], v241 offset:5120
	ds_read_b64_tr_b16 v[202:203], v242 offset:41984
	ds_read_b64_tr_b16 v[204:205], v243 offset:41984
	ds_read_b64_tr_b16 v[206:207], v234 offset:9216
	ds_read_b64_tr_b16 v[208:209], v235 offset:9216
	v_mfma_f32_32x32x16_bf16 v[0:15], v[214:217], v[210:213], v[0:15]
	v_mfma_f32_32x32x16_bf16 v[16:31], v[144:147], v[210:213], v[16:31]
	v_mfma_f32_32x32x16_bf16 v[32:47], v[148:151], v[210:213], v[32:47]
	v_mfma_f32_32x32x16_bf16 v[48:63], v[152:155], v[210:213], v[48:63]
	s_waitcnt lgkmcnt(10)
	v_mfma_f32_32x32x16_bf16 v[0:15], v[184:187], v[156:159], v[0:15]
	ds_read_b64_tr_b16 v[214:215], v236 offset:9216
	ds_read_b64_tr_b16 v[216:217], v237 offset:9216
	s_waitcnt lgkmcnt(10)
	v_mfma_f32_32x32x16_bf16 v[16:31], v[188:191], v[156:159], v[16:31]
	ds_read_b64_tr_b16 v[144:145], v238 offset:9216
	ds_read_b64_tr_b16 v[146:147], v239 offset:9216
	s_waitcnt lgkmcnt(10)
	v_mfma_f32_32x32x16_bf16 v[32:47], v[192:195], v[156:159], v[32:47]
	ds_read_b64_tr_b16 v[148:149], v240 offset:9216
	ds_read_b64_tr_b16 v[150:151], v241 offset:9216
	s_waitcnt lgkmcnt(10)
	v_mfma_f32_32x32x16_bf16 v[48:63], v[196:199], v[156:159], v[48:63]
	ds_read_b64_tr_b16 v[152:153], v242 offset:46080
	ds_read_b64_tr_b16 v[154:155], v243 offset:46080
	s_waitcnt lgkmcnt(8)
	v_mfma_f32_32x32x16_bf16 v[0:15], v[206:209], v[202:205], v[0:15]
	ds_read_b64_tr_b16 v[210:211], v234 offset:13312
	ds_read_b64_tr_b16 v[212:213], v235 offset:13312
	ds_read_b64_tr_b16 v[184:185], v236 offset:13312
	ds_read_b64_tr_b16 v[186:187], v237 offset:13312
	s_waitcnt lgkmcnt(10)
	v_mfma_f32_32x32x16_bf16 v[16:31], v[214:217], v[202:205], v[16:31]
	ds_read_b64_tr_b16 v[188:189], v238 offset:13312
	ds_read_b64_tr_b16 v[190:191], v239 offset:13312
	s_waitcnt lgkmcnt(10)
	v_mfma_f32_32x32x16_bf16 v[32:47], v[144:147], v[202:205], v[32:47]
	ds_read_b64_tr_b16 v[192:193], v240 offset:13312
	ds_read_b64_tr_b16 v[194:195], v241 offset:13312
	s_waitcnt lgkmcnt(10)
	v_mfma_f32_32x32x16_bf16 v[48:63], v[148:151], v[202:205], v[48:63]
	ds_read_b128 v[196:199], v255 offset:0
	ds_read_b128 v[156:159], v255 offset:32
	s_waitcnt lgkmcnt(8)
	v_mfma_f32_32x32x16_bf16 v[0:15], v[210:213], v[152:155], v[0:15]
	ds_read_b128 v[206:209], v255 offset:64
	ds_read_b128 v[214:217], v255 offset:96
	ds_read_b128 v[144:147], v255 offset:128
	ds_read_b128 v[148:151], v255 offset:160
	s_waitcnt lgkmcnt(10)
	v_mfma_f32_32x32x16_bf16 v[16:31], v[184:187], v[152:155], v[16:31]
	ds_read_b128 v[202:205], v255 offset:192
	ds_read_b128 v[210:213], v255 offset:224
	s_waitcnt lgkmcnt(10)
	v_mfma_f32_32x32x16_bf16 v[32:47], v[188:191], v[152:155], v[32:47]
	ds_read_b128 v[184:187], v255 offset:256
	ds_read_b128 v[188:191], v255 offset:288
	s_waitcnt lgkmcnt(10)
	v_mfma_f32_32x32x16_bf16 v[48:63], v[192:195], v[152:155], v[48:63]
	ds_read_b128 v[192:195], v255 offset:320
	ds_read_b128 v[152:155], v255 offset:352
	s_waitcnt lgkmcnt(11)
	v_pk_mul_f32 v[0:1], v[0:1], v[196:197]
	v_pk_mul_f32 v[2:3], v[2:3], v[198:199]
	ds_read_b128 v[196:199], v255 offset:384
	s_waitcnt lgkmcnt(11)
	v_pk_mul_f32 v[4:5], v[4:5], v[156:157]
	v_pk_mul_f32 v[6:7], v[6:7], v[158:159]
	ds_read_b128 v[156:159], v255 offset:416
	s_waitcnt lgkmcnt(11)
	v_pk_mul_f32 v[8:9], v[8:9], v[206:207]
	v_pk_mul_f32 v[10:11], v[10:11], v[208:209]
	ds_read_b128 v[206:209], v255 offset:448
	s_waitcnt lgkmcnt(11)
	v_pk_mul_f32 v[12:13], v[12:13], v[214:215]
	v_pk_mul_f32 v[14:15], v[14:15], v[216:217]
	ds_read_b128 v[214:217], v255 offset:480
	s_waitcnt lgkmcnt(11)
	v_pk_mul_f32 v[16:17], v[16:17], v[144:145]
	v_pk_mul_f32 v[18:19], v[18:19], v[146:147]
	s_waitcnt lgkmcnt(10)
	v_pk_mul_f32 v[20:21], v[20:21], v[148:149]
	v_pk_mul_f32 v[22:23], v[22:23], v[150:151]
	s_waitcnt lgkmcnt(9)
	v_pk_mul_f32 v[24:25], v[24:25], v[202:203]
	v_pk_mul_f32 v[26:27], v[26:27], v[204:205]
	s_waitcnt lgkmcnt(8)
	v_pk_mul_f32 v[28:29], v[28:29], v[210:211]
	v_pk_mul_f32 v[30:31], v[30:31], v[212:213]
	s_waitcnt lgkmcnt(7)
	v_pk_mul_f32 v[32:33], v[32:33], v[184:185]
	v_pk_mul_f32 v[34:35], v[34:35], v[186:187]
	s_waitcnt lgkmcnt(6)
	v_pk_mul_f32 v[36:37], v[36:37], v[188:189]
	v_pk_mul_f32 v[38:39], v[38:39], v[190:191]
	s_waitcnt lgkmcnt(5)
	v_pk_mul_f32 v[40:41], v[40:41], v[192:193]
	v_pk_mul_f32 v[42:43], v[42:43], v[194:195]
	s_waitcnt lgkmcnt(4)
	v_pk_mul_f32 v[44:45], v[44:45], v[152:153]
	v_pk_mul_f32 v[46:47], v[46:47], v[154:155]
	s_waitcnt lgkmcnt(3)
	v_pk_mul_f32 v[48:49], v[48:49], v[196:197]
	v_pk_mul_f32 v[50:51], v[50:51], v[198:199]
	s_waitcnt lgkmcnt(2)
	v_pk_mul_f32 v[52:53], v[52:53], v[156:157]
	v_pk_mul_f32 v[54:55], v[54:55], v[158:159]
	s_waitcnt lgkmcnt(1)
	v_pk_mul_f32 v[56:57], v[56:57], v[206:207]
	v_pk_mul_f32 v[58:59], v[58:59], v[208:209]
	s_waitcnt lgkmcnt(0)
	v_pk_mul_f32 v[60:61], v[60:61], v[214:215]
	v_pk_mul_f32 v[62:63], v[62:63], v[216:217]
	v_add_u32_e32 v171, s33, v171
	s_barrier
	ds_read_b128 v[64:67], v248
	ds_read_b128 v[144:147], v226 offset:17408
	ds_read_b128 v[68:71], v248 offset:32
	ds_read_b128 v[148:151], v227 offset:17408
	ds_read_b128 v[72:75], v248 offset:64
	ds_read_b128 v[152:155], v228 offset:17408
	ds_read_b128 v[76:79], v248 offset:96
	ds_read_b128 v[156:159], v229 offset:17408
	ds_read_b128 v[80:83], v248 offset:128
	ds_read_b128 v[184:187], v230 offset:17408
	ds_read_b128 v[84:87], v248 offset:160
	ds_read_b128 v[188:191], v231 offset:17408
	s_waitcnt lgkmcnt(10)
	v_mfma_f32_32x32x16_bf16 v[96:111], v[144:147], v[64:67], 0
	ds_read_b128 v[88:91], v248 offset:192
	ds_read_b128 v[192:195], v232 offset:17408
	s_waitcnt lgkmcnt(10)
	v_mfma_f32_32x32x16_bf16 v[96:111], v[148:151], v[68:71], v[96:111]
	ds_read_b128 v[92:95], v248 offset:224
	ds_read_b128 v[196:199], v233 offset:17408
	s_waitcnt lgkmcnt(10)
	v_mfma_f32_32x32x16_bf16 v[96:111], v[152:155], v[72:75], v[96:111]
	ds_read_b64_tr_b16 v[202:203], v244 offset:50176
	ds_read_b64_tr_b16 v[204:205], v245 offset:50176
	s_waitcnt lgkmcnt(10)
	v_mfma_f32_32x32x16_bf16 v[96:111], v[156:159], v[76:79], v[96:111]
	ds_read_b64_tr_b16 v[206:207], v244 offset:54272
	ds_read_b64_tr_b16 v[208:209], v245 offset:54272
	s_waitcnt lgkmcnt(10)
	v_mfma_f32_32x32x16_bf16 v[96:111], v[184:187], v[80:83], v[96:111]
	ds_read2_b64 v[210:213], v252 offset0:0 offset1:2
	ds_read2_b64 v[214:217], v252 offset0:4 offset1:6
	s_waitcnt lgkmcnt(10)
	v_mfma_f32_32x32x16_bf16 v[96:111], v[188:191], v[84:87], v[96:111]
	ds_read2_b64 v[144:147], v252 offset0:8 offset1:10
	ds_read2_b64 v[148:151], v252 offset0:12 offset1:14
	s_waitcnt lgkmcnt(10)
	v_mfma_f32_32x32x16_bf16 v[96:111], v[192:195], v[88:91], v[96:111]
	ds_read2_b64 v[152:155], v252 offset0:16 offset1:18
	ds_read2_b64 v[156:159], v252 offset0:20 offset1:22
	s_waitcnt lgkmcnt(10)
	v_mfma_f32_32x32x16_bf16 v[96:111], v[196:199], v[92:95], v[96:111]
	ds_read2_b64 v[184:187], v252 offset0:24 offset1:26
	ds_read2_b64 v[188:191], v252 offset0:28 offset1:30
	s_waitcnt lgkmcnt(10)
	s_nop 8
	v_cndmask_b32_e64 v96, v96, 0, s[38:39]
	v_cndmask_b32_e64 v97, v97, 0, s[40:41]
	v_cndmask_b32_e64 v98, v98, 0, s[42:43]
	v_cndmask_b32_e64 v99, v99, 0, s[44:45]
	v_cndmask_b32_e64 v100, v100, 0, s[46:47]
	v_cndmask_b32_e64 v101, v101, 0, s[48:49]
	v_cndmask_b32_e64 v102, v102, 0, s[50:51]
	v_cndmask_b32_e64 v103, v103, 0, s[52:53]
	v_cndmask_b32_e64 v104, v104, 0, s[54:55]
	v_cndmask_b32_e64 v105, v105, 0, s[56:57]
	v_cndmask_b32_e64 v106, v106, 0, s[58:59]
	v_cndmask_b32_e64 v107, v107, 0, s[60:61]
	v_cndmask_b32_e64 v108, v108, 0, s[62:63]
	v_cndmask_b32_e64 v109, v109, 0, s[64:65]
	v_cndmask_b32_e64 v110, v110, 0, s[66:67]
	v_cndmask_b32_e64 v111, v111, 0, s[68:69]
	v_cvt_pk_bf16_f32 v96, v96, v97
	v_cvt_pk_bf16_f32 v97, v98, v99
	v_cvt_pk_bf16_f32 v98, v100, v101
	v_cvt_pk_bf16_f32 v99, v102, v103
	v_cvt_pk_bf16_f32 v100, v104, v105
	v_cvt_pk_bf16_f32 v101, v106, v107
	v_cvt_pk_bf16_f32 v102, v108, v109
	v_cvt_pk_bf16_f32 v103, v110, v111
	v_mfma_f32_32x32x16_bf16 v[128:143], v[202:205], v[96:99], 0
	s_waitcnt lgkmcnt(8)
	v_mfma_f32_32x32x16_bf16 v[128:143], v[206:209], v[100:103], v[128:143]
	v_cvt_pk_bf16_f32 v218, v0, v1
	v_cvt_pk_bf16_f32 v219, v2, v3
	v_cvt_pk_bf16_f32 v220, v4, v5
	v_cvt_pk_bf16_f32 v221, v6, v7
	s_waitcnt lgkmcnt(7)
	s_nop 1
	v_mfma_f32_32x32x16_bf16 v[128:143], v[218:221], v[210:213], v[128:143]
	v_cvt_pk_bf16_f32 v222, v8, v9
	v_cvt_pk_bf16_f32 v223, v10, v11
	v_cvt_pk_bf16_f32 v224, v12, v13
	v_cvt_pk_bf16_f32 v225, v14, v15
	s_waitcnt lgkmcnt(6)
	s_nop 1
	v_mfma_f32_32x32x16_bf16 v[128:143], v[222:225], v[214:217], v[128:143]
	v_cvt_pk_bf16_f32 v218, v16, v17
	v_cvt_pk_bf16_f32 v219, v18, v19
	v_cvt_pk_bf16_f32 v220, v20, v21
	v_cvt_pk_bf16_f32 v221, v22, v23
	s_waitcnt lgkmcnt(5)
	s_nop 1
	v_mfma_f32_32x32x16_bf16 v[128:143], v[218:221], v[144:147], v[128:143]
	v_cvt_pk_bf16_f32 v222, v24, v25
	v_cvt_pk_bf16_f32 v223, v26, v27
	v_cvt_pk_bf16_f32 v224, v28, v29
	v_cvt_pk_bf16_f32 v225, v30, v31
	s_waitcnt lgkmcnt(4)
	s_nop 1
	v_mfma_f32_32x32x16_bf16 v[128:143], v[222:225], v[148:151], v[128:143]
	v_cvt_pk_bf16_f32 v218, v32, v33
	v_cvt_pk_bf16_f32 v219, v34, v35
	v_cvt_pk_bf16_f32 v220, v36, v37
	v_cvt_pk_bf16_f32 v221, v38, v39
	s_waitcnt lgkmcnt(3)
	s_nop 1
	v_mfma_f32_32x32x16_bf16 v[128:143], v[218:221], v[152:155], v[128:143]
	v_cvt_pk_bf16_f32 v222, v40, v41
	v_cvt_pk_bf16_f32 v223, v42, v43
	v_cvt_pk_bf16_f32 v224, v44, v45
	v_cvt_pk_bf16_f32 v225, v46, v47
	s_waitcnt lgkmcnt(2)
	s_nop 1
	v_mfma_f32_32x32x16_bf16 v[128:143], v[222:225], v[156:159], v[128:143]
	v_cvt_pk_bf16_f32 v218, v48, v49
	v_cvt_pk_bf16_f32 v219, v50, v51
	v_cvt_pk_bf16_f32 v220, v52, v53
	v_cvt_pk_bf16_f32 v221, v54, v55
	s_waitcnt lgkmcnt(1)
	s_nop 1
	v_mfma_f32_32x32x16_bf16 v[128:143], v[218:221], v[184:187], v[128:143]
	v_cvt_pk_bf16_f32 v222, v56, v57
	v_cvt_pk_bf16_f32 v223, v58, v59
	v_cvt_pk_bf16_f32 v224, v60, v61
	v_cvt_pk_bf16_f32 v225, v62, v63
	s_waitcnt lgkmcnt(0)
	s_nop 1
	v_mfma_f32_32x32x16_bf16 v[128:143], v[222:225], v[188:191], v[128:143]
	ds_read_b128 v[64:67], v250
	ds_read_b128 v[192:195], v226 offset:17408
	ds_read_b128 v[68:71], v250 offset:32
	ds_read_b128 v[196:199], v227 offset:17408
	ds_read_b128 v[72:75], v250 offset:64
	ds_read_b128 v[202:205], v228 offset:17408
	ds_read_b128 v[76:79], v250 offset:96
	ds_read_b128 v[206:209], v229 offset:17408
	ds_read_b128 v[80:83], v250 offset:128
	ds_read_b128 v[210:213], v230 offset:17408
	ds_read_b128 v[84:87], v250 offset:160
	ds_read_b128 v[214:217], v231 offset:17408
	s_waitcnt lgkmcnt(11)
	v_cvt_pk_bf16_f32 v218, v128, v129
	v_cvt_pk_bf16_f32 v219, v130, v131
	v_cvt_pk_bf16_f32 v220, v132, v133
	v_cvt_pk_bf16_f32 v221, v134, v135
	v_cvt_pk_bf16_f32 v222, v136, v137
	v_cvt_pk_bf16_f32 v223, v138, v139
	v_cvt_pk_bf16_f32 v224, v140, v141
	v_cvt_pk_bf16_f32 v225, v142, v143
	ds_write2_b64 v168, v[218:219], v[220:221] offset1:2
	ds_write2_b64 v168, v[222:223], v[224:225] offset0:4 offset1:6
	ds_read_b128 v[218:221], v169
	ds_read_b128 v[222:225], v170
	v_add_u32_e32 v183, s71, v171
	v_add_u32_e32 v201, s72, v171
	s_waitcnt lgkmcnt(0)
	global_store_dwordx4 v183, v[218:221], s[14:15]
	global_store_dwordx4 v201, v[222:225], s[14:15]
	ds_read_b128 v[88:91], v250 offset:192
	ds_read_b128 v[144:147], v232 offset:17408
	ds_read_b128 v[92:95], v250 offset:224
	ds_read_b128 v[148:151], v233 offset:17408
	ds_read_b128 v[152:155], v226 offset:25600
	ds_read_b128 v[156:159], v227 offset:25600
	ds_read_b128 v[184:187], v228 offset:25600
	ds_read_b128 v[188:191], v229 offset:25600
	v_mfma_f32_32x32x16_bf16 v[96:111], v[192:195], v[64:67], 0
	ds_read_b128 v[192:195], v230 offset:25600
	v_mfma_f32_32x32x16_bf16 v[96:111], v[196:199], v[68:71], v[96:111]
	ds_read_b128 v[196:199], v231 offset:25600
	v_mfma_f32_32x32x16_bf16 v[96:111], v[202:205], v[72:75], v[96:111]
	ds_read_b128 v[202:205], v232 offset:25600
	v_mfma_f32_32x32x16_bf16 v[96:111], v[206:209], v[76:79], v[96:111]
	ds_read_b128 v[206:209], v233 offset:25600
	v_mfma_f32_32x32x16_bf16 v[96:111], v[210:213], v[80:83], v[96:111]
	v_mfma_f32_32x32x16_bf16 v[96:111], v[214:217], v[84:87], v[96:111]
	s_waitcnt lgkmcnt(10)
	v_mfma_f32_32x32x16_bf16 v[96:111], v[144:147], v[88:91], v[96:111]
	ds_read_b64_tr_b16 v[210:211], v244 offset:50176
	ds_read_b64_tr_b16 v[212:213], v245 offset:50176
	s_waitcnt lgkmcnt(10)
	v_mfma_f32_32x32x16_bf16 v[96:111], v[148:151], v[92:95], v[96:111]
	ds_read_b64_tr_b16 v[214:215], v244 offset:54272
	ds_read_b64_tr_b16 v[216:217], v245 offset:54272
	s_waitcnt lgkmcnt(11)
	v_mfma_f32_32x32x16_bf16 v[112:127], v[152:155], v[64:67], 0
	s_waitcnt lgkmcnt(10)
	v_mfma_f32_32x32x16_bf16 v[112:127], v[156:159], v[68:71], v[112:127]
	ds_read_b64_tr_b16 v[144:145], v244 offset:58368
	ds_read_b64_tr_b16 v[146:147], v245 offset:58368
	s_waitcnt lgkmcnt(11)
	v_mfma_f32_32x32x16_bf16 v[112:127], v[184:187], v[72:75], v[112:127]
	s_waitcnt lgkmcnt(10)
	v_mfma_f32_32x32x16_bf16 v[112:127], v[188:191], v[76:79], v[112:127]
	ds_read_b64_tr_b16 v[148:149], v244 offset:62464
	ds_read_b64_tr_b16 v[150:151], v245 offset:62464
	s_waitcnt lgkmcnt(11)
	v_mfma_f32_32x32x16_bf16 v[112:127], v[192:195], v[80:83], v[112:127]
	ds_read2_b64 v[152:155], v254 offset0:0 offset1:2
	s_waitcnt lgkmcnt(11)
	v_mfma_f32_32x32x16_bf16 v[112:127], v[196:199], v[84:87], v[112:127]
	ds_read2_b64 v[156:159], v254 offset0:4 offset1:6
	s_waitcnt lgkmcnt(11)
	v_mfma_f32_32x32x16_bf16 v[112:127], v[202:205], v[88:91], v[112:127]
	ds_read2_b64 v[184:187], v254 offset0:8 offset1:10
	s_waitcnt lgkmcnt(11)
	v_mfma_f32_32x32x16_bf16 v[112:127], v[206:209], v[92:95], v[112:127]
	ds_read2_b64 v[188:191], v254 offset0:12 offset1:14
	s_waitcnt lgkmcnt(10)
	v_cvt_pk_bf16_f32 v96, v96, v97
	v_cvt_pk_bf16_f32 v97, v98, v99
	v_cvt_pk_bf16_f32 v98, v100, v101
	v_cvt_pk_bf16_f32 v99, v102, v103
	v_cvt_pk_bf16_f32 v100, v104, v105
	v_cvt_pk_bf16_f32 v101, v106, v107
	v_cvt_pk_bf16_f32 v102, v108, v109
	v_cvt_pk_bf16_f32 v103, v110, v111
	s_nop 1
	v_cndmask_b32_e64 v112, v112, 0, s[38:39]
	v_cndmask_b32_e64 v113, v113, 0, s[40:41]
	v_cndmask_b32_e64 v114, v114, 0, s[42:43]
	v_cndmask_b32_e64 v115, v115, 0, s[44:45]
	v_cndmask_b32_e64 v116, v116, 0, s[46:47]
	v_cndmask_b32_e64 v117, v117, 0, s[48:49]
	v_cndmask_b32_e64 v118, v118, 0, s[50:51]
	v_cndmask_b32_e64 v119, v119, 0, s[52:53]
	v_cndmask_b32_e64 v120, v120, 0, s[54:55]
	v_cndmask_b32_e64 v121, v121, 0, s[56:57]
	v_cndmask_b32_e64 v122, v122, 0, s[58:59]
	v_cndmask_b32_e64 v123, v123, 0, s[60:61]
	v_cndmask_b32_e64 v124, v124, 0, s[62:63]
	v_cndmask_b32_e64 v125, v125, 0, s[64:65]
	v_cndmask_b32_e64 v126, v126, 0, s[66:67]
	v_cndmask_b32_e64 v127, v127, 0, s[68:69]
	v_cvt_pk_bf16_f32 v112, v112, v113
	v_cvt_pk_bf16_f32 v113, v114, v115
	v_cvt_pk_bf16_f32 v114, v116, v117
	v_cvt_pk_bf16_f32 v115, v118, v119
	v_cvt_pk_bf16_f32 v116, v120, v121
	v_cvt_pk_bf16_f32 v117, v122, v123
	v_cvt_pk_bf16_f32 v118, v124, v125
	v_cvt_pk_bf16_f32 v119, v126, v127
	ds_read2_b64 v[192:195], v254 offset0:16 offset1:18
	ds_read2_b64 v[196:199], v254 offset0:20 offset1:22
	v_mfma_f32_32x32x16_bf16 v[128:143], v[210:213], v[96:99], 0
	s_waitcnt lgkmcnt(10)
	v_mfma_f32_32x32x16_bf16 v[128:143], v[214:217], v[100:103], v[128:143]
	ds_read2_b64 v[202:205], v254 offset0:24 offset1:26
	ds_read2_b64 v[206:209], v254 offset0:28 offset1:30
	s_waitcnt lgkmcnt(10)
	v_mfma_f32_32x32x16_bf16 v[128:143], v[144:147], v[112:115], v[128:143]
	ds_read_b64_tr_b16 v[210:211], v242 offset:50176
	ds_read_b64_tr_b16 v[212:213], v243 offset:50176
	s_waitcnt lgkmcnt(10)
	v_mfma_f32_32x32x16_bf16 v[128:143], v[148:151], v[116:119], v[128:143]
	v_cvt_pk_bf16_f32 v218, v0, v1
	v_cvt_pk_bf16_f32 v219, v2, v3
	v_cvt_pk_bf16_f32 v220, v4, v5
	v_cvt_pk_bf16_f32 v221, v6, v7
	ds_read_b64_tr_b16 v[214:215], v234 offset:17408
	ds_read_b64_tr_b16 v[216:217], v235 offset:17408
	s_waitcnt lgkmcnt(11)
	s_nop 1
	v_mfma_f32_32x32x16_bf16 v[128:143], v[218:221], v[152:155], v[128:143]
	v_cvt_pk_bf16_f32 v222, v8, v9
	v_cvt_pk_bf16_f32 v223, v10, v11
	v_cvt_pk_bf16_f32 v224, v12, v13
	v_cvt_pk_bf16_f32 v225, v14, v15
	s_waitcnt lgkmcnt(10)
	s_nop 1
	v_mfma_f32_32x32x16_bf16 v[128:143], v[222:225], v[156:159], v[128:143]
	v_cvt_pk_bf16_f32 v218, v16, v17
	v_cvt_pk_bf16_f32 v219, v18, v19
	v_cvt_pk_bf16_f32 v220, v20, v21
	v_cvt_pk_bf16_f32 v221, v22, v23
	ds_read_b64_tr_b16 v[144:145], v236 offset:17408
	ds_read_b64_tr_b16 v[146:147], v237 offset:17408
	s_waitcnt lgkmcnt(11)
	s_nop 1
	v_mfma_f32_32x32x16_bf16 v[128:143], v[218:221], v[184:187], v[128:143]
	v_cvt_pk_bf16_f32 v222, v24, v25
	v_cvt_pk_bf16_f32 v223, v26, v27
	v_cvt_pk_bf16_f32 v224, v28, v29
	v_cvt_pk_bf16_f32 v225, v30, v31
	s_waitcnt lgkmcnt(10)
	s_nop 1
	v_mfma_f32_32x32x16_bf16 v[128:143], v[222:225], v[188:191], v[128:143]
	v_cvt_pk_bf16_f32 v218, v32, v33
	v_cvt_pk_bf16_f32 v219, v34, v35
	v_cvt_pk_bf16_f32 v220, v36, v37
	v_cvt_pk_bf16_f32 v221, v38, v39
	ds_read_b64_tr_b16 v[148:149], v238 offset:17408
	ds_read_b64_tr_b16 v[150:151], v239 offset:17408
	s_waitcnt lgkmcnt(11)
	s_nop 1
	v_mfma_f32_32x32x16_bf16 v[128:143], v[218:221], v[192:195], v[128:143]
	v_cvt_pk_bf16_f32 v222, v40, v41
	v_cvt_pk_bf16_f32 v223, v42, v43
	v_cvt_pk_bf16_f32 v224, v44, v45
	v_cvt_pk_bf16_f32 v225, v46, v47
	s_waitcnt lgkmcnt(10)
	s_nop 1
	v_mfma_f32_32x32x16_bf16 v[128:143], v[222:225], v[196:199], v[128:143]
	v_cvt_pk_bf16_f32 v218, v48, v49
	v_cvt_pk_bf16_f32 v219, v50, v51
	v_cvt_pk_bf16_f32 v220, v52, v53
	v_cvt_pk_bf16_f32 v221, v54, v55
	ds_read_b64_tr_b16 v[152:153], v240 offset:17408
	ds_read_b64_tr_b16 v[154:155], v241 offset:17408
	s_waitcnt lgkmcnt(11)
	s_nop 1
	v_mfma_f32_32x32x16_bf16 v[128:143], v[218:221], v[202:205], v[128:143]
	v_cvt_pk_bf16_f32 v222, v56, v57
	v_cvt_pk_bf16_f32 v223, v58, v59
	v_cvt_pk_bf16_f32 v224, v60, v61
	v_cvt_pk_bf16_f32 v225, v62, v63
	s_waitcnt lgkmcnt(10)
	s_nop 1
	v_mfma_f32_32x32x16_bf16 v[128:143], v[222:225], v[206:209], v[128:143]
	ds_read_b64_tr_b16 v[156:157], v242 offset:54272
	ds_read_b64_tr_b16 v[158:159], v243 offset:54272
	s_waitcnt lgkmcnt(10)
	s_nop 8
	v_cvt_pk_bf16_f32 v218, v128, v129
	v_cvt_pk_bf16_f32 v219, v130, v131
	v_cvt_pk_bf16_f32 v220, v132, v133
	v_cvt_pk_bf16_f32 v221, v134, v135
	v_cvt_pk_bf16_f32 v222, v136, v137
	v_cvt_pk_bf16_f32 v223, v138, v139
	v_cvt_pk_bf16_f32 v224, v140, v141
	v_cvt_pk_bf16_f32 v225, v142, v143
	ds_write2_b64 v168, v[218:219], v[220:221] offset1:2
	ds_write2_b64 v168, v[222:223], v[224:225] offset0:4 offset1:6
	ds_read_b128 v[218:221], v169
	ds_read_b128 v[222:225], v170
	v_add_u32_e32 v183, s73, v171
	v_add_u32_e32 v201, s75, v171
	s_waitcnt lgkmcnt(0)
	global_store_dwordx4 v183, v[218:221], s[14:15]
	global_store_dwordx4 v201, v[222:225], s[14:15]
	ds_read_b64_tr_b16 v[184:185], v234 offset:21504
	ds_read_b64_tr_b16 v[186:187], v235 offset:21504
	ds_read_b64_tr_b16 v[188:189], v236 offset:21504
	ds_read_b64_tr_b16 v[190:191], v237 offset:21504
	ds_read_b64_tr_b16 v[192:193], v238 offset:21504
	ds_read_b64_tr_b16 v[194:195], v239 offset:21504
	ds_read_b64_tr_b16 v[196:197], v240 offset:21504
	ds_read_b64_tr_b16 v[198:199], v241 offset:21504
	ds_read_b64_tr_b16 v[202:203], v242 offset:58368
	ds_read_b64_tr_b16 v[204:205], v243 offset:58368
	ds_read_b64_tr_b16 v[206:207], v234 offset:25600
	ds_read_b64_tr_b16 v[208:209], v235 offset:25600
	v_mfma_f32_32x32x16_bf16 v[0:15], v[214:217], v[210:213], v[0:15]
	v_mfma_f32_32x32x16_bf16 v[16:31], v[144:147], v[210:213], v[16:31]
	v_mfma_f32_32x32x16_bf16 v[32:47], v[148:151], v[210:213], v[32:47]
	v_mfma_f32_32x32x16_bf16 v[48:63], v[152:155], v[210:213], v[48:63]
	s_waitcnt lgkmcnt(10)
	v_mfma_f32_32x32x16_bf16 v[0:15], v[184:187], v[156:159], v[0:15]
	ds_read_b64_tr_b16 v[214:215], v236 offset:25600
	ds_read_b64_tr_b16 v[216:217], v237 offset:25600
	s_waitcnt lgkmcnt(10)
	v_mfma_f32_32x32x16_bf16 v[16:31], v[188:191], v[156:159], v[16:31]
	ds_read_b64_tr_b16 v[144:145], v238 offset:25600
	ds_read_b64_tr_b16 v[146:147], v239 offset:25600
	s_waitcnt lgkmcnt(10)
	v_mfma_f32_32x32x16_bf16 v[32:47], v[192:195], v[156:159], v[32:47]
	ds_read_b64_tr_b16 v[148:149], v240 offset:25600
	ds_read_b64_tr_b16 v[150:151], v241 offset:25600
	s_waitcnt lgkmcnt(10)
	v_mfma_f32_32x32x16_bf16 v[48:63], v[196:199], v[156:159], v[48:63]
	ds_read_b64_tr_b16 v[152:153], v242 offset:62464
	ds_read_b64_tr_b16 v[154:155], v243 offset:62464
	s_waitcnt lgkmcnt(8)
	v_mfma_f32_32x32x16_bf16 v[0:15], v[206:209], v[202:205], v[0:15]
	ds_read_b64_tr_b16 v[210:211], v234 offset:29696
	ds_read_b64_tr_b16 v[212:213], v235 offset:29696
	ds_read_b64_tr_b16 v[184:185], v236 offset:29696
	ds_read_b64_tr_b16 v[186:187], v237 offset:29696
	s_waitcnt lgkmcnt(10)
	v_mfma_f32_32x32x16_bf16 v[16:31], v[214:217], v[202:205], v[16:31]
	ds_read_b64_tr_b16 v[188:189], v238 offset:29696
	ds_read_b64_tr_b16 v[190:191], v239 offset:29696
	s_waitcnt lgkmcnt(10)
	v_mfma_f32_32x32x16_bf16 v[32:47], v[144:147], v[202:205], v[32:47]
	ds_read_b64_tr_b16 v[192:193], v240 offset:29696
	ds_read_b64_tr_b16 v[194:195], v241 offset:29696
	s_waitcnt lgkmcnt(10)
	v_mfma_f32_32x32x16_bf16 v[48:63], v[148:151], v[202:205], v[48:63]
	ds_read_b128 v[196:199], v255 offset:512
	ds_read_b128 v[156:159], v255 offset:544
	s_waitcnt lgkmcnt(8)
	v_mfma_f32_32x32x16_bf16 v[0:15], v[210:213], v[152:155], v[0:15]
	ds_read_b128 v[206:209], v255 offset:576
	ds_read_b128 v[214:217], v255 offset:608
	ds_read_b128 v[144:147], v255 offset:640
	ds_read_b128 v[148:151], v255 offset:672
	s_waitcnt lgkmcnt(10)
	v_mfma_f32_32x32x16_bf16 v[16:31], v[184:187], v[152:155], v[16:31]
	ds_read_b128 v[202:205], v255 offset:704
	ds_read_b128 v[210:213], v255 offset:736
	s_waitcnt lgkmcnt(10)
	v_mfma_f32_32x32x16_bf16 v[32:47], v[188:191], v[152:155], v[32:47]
	ds_read_b128 v[184:187], v255 offset:768
	ds_read_b128 v[188:191], v255 offset:800
	s_waitcnt lgkmcnt(10)
	v_mfma_f32_32x32x16_bf16 v[48:63], v[192:195], v[152:155], v[48:63]
	ds_read_b128 v[192:195], v255 offset:832
	ds_read_b128 v[152:155], v255 offset:864
	s_waitcnt lgkmcnt(11)
	v_pk_mul_f32 v[0:1], v[0:1], v[196:197]
	v_pk_mul_f32 v[2:3], v[2:3], v[198:199]
	ds_read_b128 v[196:199], v255 offset:896
	s_waitcnt lgkmcnt(11)
	v_pk_mul_f32 v[4:5], v[4:5], v[156:157]
	v_pk_mul_f32 v[6:7], v[6:7], v[158:159]
	ds_read_b128 v[156:159], v255 offset:928
	s_waitcnt lgkmcnt(11)
	v_pk_mul_f32 v[8:9], v[8:9], v[206:207]
	v_pk_mul_f32 v[10:11], v[10:11], v[208:209]
	ds_read_b128 v[206:209], v255 offset:960
	s_waitcnt lgkmcnt(11)
	v_pk_mul_f32 v[12:13], v[12:13], v[214:215]
	v_pk_mul_f32 v[14:15], v[14:15], v[216:217]
	ds_read_b128 v[214:217], v255 offset:992
	s_waitcnt lgkmcnt(11)
	v_pk_mul_f32 v[16:17], v[16:17], v[144:145]
	v_pk_mul_f32 v[18:19], v[18:19], v[146:147]
	s_waitcnt lgkmcnt(10)
	v_pk_mul_f32 v[20:21], v[20:21], v[148:149]
	v_pk_mul_f32 v[22:23], v[22:23], v[150:151]
	s_waitcnt lgkmcnt(9)
	v_pk_mul_f32 v[24:25], v[24:25], v[202:203]
	v_pk_mul_f32 v[26:27], v[26:27], v[204:205]
	s_waitcnt lgkmcnt(8)
	v_pk_mul_f32 v[28:29], v[28:29], v[210:211]
	v_pk_mul_f32 v[30:31], v[30:31], v[212:213]
	s_waitcnt lgkmcnt(7)
	v_pk_mul_f32 v[32:33], v[32:33], v[184:185]
	v_pk_mul_f32 v[34:35], v[34:35], v[186:187]
	s_waitcnt lgkmcnt(6)
	v_pk_mul_f32 v[36:37], v[36:37], v[188:189]
	v_pk_mul_f32 v[38:39], v[38:39], v[190:191]
	s_waitcnt lgkmcnt(5)
	v_pk_mul_f32 v[40:41], v[40:41], v[192:193]
	v_pk_mul_f32 v[42:43], v[42:43], v[194:195]
	s_waitcnt lgkmcnt(4)
	v_pk_mul_f32 v[44:45], v[44:45], v[152:153]
	v_pk_mul_f32 v[46:47], v[46:47], v[154:155]
	s_waitcnt lgkmcnt(3)
	v_pk_mul_f32 v[48:49], v[48:49], v[196:197]
	v_pk_mul_f32 v[50:51], v[50:51], v[198:199]
	s_waitcnt lgkmcnt(2)
	v_pk_mul_f32 v[52:53], v[52:53], v[156:157]
	v_pk_mul_f32 v[54:55], v[54:55], v[158:159]
	s_waitcnt lgkmcnt(1)
	v_pk_mul_f32 v[56:57], v[56:57], v[206:207]
	v_pk_mul_f32 v[58:59], v[58:59], v[208:209]
	s_waitcnt lgkmcnt(0)
	v_pk_mul_f32 v[60:61], v[60:61], v[214:215]
	v_pk_mul_f32 v[62:63], v[62:63], v[216:217]
	v_add_u32_e32 v171, s33, v171
	s_barrier
	s_add_u32 s70, s70, 1
	s_cmp_lt_u32 s70, 32
	s_cbranch_scc1 .Lh2_mfma_loop
	s_branch .Lh2_done
.Lh2_done:
	s_barrier
	s_branch .LBB0_445
	s_nop 0
	s_nop 0
	s_nop 0
	s_nop 0
	s_nop 0
	s_nop 0
	s_nop 0
	s_nop 0
	s_nop 0
	s_nop 0
	s_nop 0
	s_nop 0
	s_nop 0
	s_nop 0
	s_nop 0
	s_nop 0
	s_nop 0
	s_nop 0
	s_nop 0
	s_nop 0
	s_nop 0
	s_nop 0
	s_nop 0
	s_nop 0
	s_nop 0
	s_nop 0
